# gemm256 K-loops rotated: barrier before the last two MFMA groups, next stage first reads + all LDS-DMA issued under them
# baseline (speedup 1.0000x reference)
; #define GLDS_STAGE(st, kt_) do { \
;         _Pragma("unroll") for (int i_ = 0; i_ < FI; ++i_) { \
;             glds16(ap + (size_t)(32 * i_) * lda + (kt_) * 64, l3a + (st) + tid * 16 + i_ * 4096); \
;             glds16(bp + (size_t)(32 * i_) * ldb + (kt_) * 64, l3a + (st) + OPB + tid * 16 + i_ * 4096); } } while (0)
; #define GLDS_STAGE(st, kt_) do { \
;         _Pragma("unroll") for (int i_ = 0; i_ < 4; ++i_) { \
;             glds16(ap + (size_t)(64 * i_) * lda + (kt_) * 64, l3a + (st) + tid * 16 + i_ * 8192); \
;             glds16(bp + (size_t)(64 * i_) * ldb + (kt_) * 64, l3a + (st) + 32768 + tid * 16 + i_ * 8192); } } while (0)
; template <class Epi>
; DEV void gemm256_tile(const bf16_t* __restrict__ A, int lda, const bf16_t* __restrict__ Bt, int ldb, int K, unsigned char* lds, const Epi& epi) {
;     ...
;     GLDS_STAGE(0, 0);
;     const int aoff = (wr * 128 + fr) * 128, boff = 32768 + (wc * 64 + fr) * 128, sw = fr & 7;
;     for (int kt = 0; kt < nk; ++kt) {
;         const int cur = (kt & 1) * 65536;
;         asm volatile("s_waitcnt vmcnt(0)" ::: "memory");
;         __syncthreads();
;         if (kt + 1 < nk) GLDS_STAGE(cur ^ 65536, kt + 1);
; #pragma unroll
;         for (int kh = 0; kh < 2; ++kh) {
;             bf16x8 bfr[4];
;             const int ch = ((kh * 4 + fq) ^ sw) << 4;
; #pragma unroll
;             for (int i = 0; i < 4; ++i) bfr[i] = *(const bf16x8*)(lds + cur + boff + i * 2048 + ch);
; #pragma unroll
;             for (int mh = 0; mh < 2; ++mh) {
;                 bf16x8 af[4];
; #pragma unroll
;                 for (int i = 0; i < 4; ++i) af[i] = *(const bf16x8*)(lds + cur + aoff + (mh * 4 + i) * 2048 + ch);
; #pragma unroll
;                 for (int mi = 0; mi < 4; ++mi)
; #pragma unroll
;                     for (int ni = 0; ni < 4; ++ni) acc[mh * 4 + mi][ni] = __builtin_amdgcn_mfma_f32_16x16x32_bf16(bfr[ni], af[mi], acc[mh * 4 + mi][ni], 0, 0, 0);
;             }
;         }
.LBB0_174:
	s_and_b32 s48, s21, 0x10000
	s_xor_b32 s49, s48, 0x10000
	v_add_u32_e32 v206, s49, v142
	v_add_u32_e32 v207, s49, v156
	s_waitcnt vmcnt(0) lgkmcnt(0)
	s_barrier
	v_or_b32_e32 v248, s48, v175
	v_add_u32_e32 v249, s48, v157
	v_add_u32_e32 v244, v248, v174
	v_add_u32_e32 v245, v249, v174
	v_add_u32_e32 v246, v248, v155
	v_add_u32_e32 v247, v249, v155
	ds_read_b128 v[176:179], v244 offset:32768
	ds_read_b128 v[212:215], v245
	ds_read_b128 v[180:183], v244 offset:34816
	ds_read_b128 v[184:187], v244 offset:36864
	ds_read_b128 v[188:191], v244 offset:38912
	ds_read_b128 v[216:219], v245 offset:2048
	ds_read_b128 v[220:223], v245 offset:4096
	ds_read_b128 v[224:227], v245 offset:6144
	v_readfirstlane_b32 s40, v206
	v_readfirstlane_b32 s44, v207
	s_nop 0
	s_add_i32 s41, s40, 0x2000
	s_add_i32 s45, s44, 0x2000
	s_add_i32 s42, s40, 0x4000
	s_add_i32 s46, s44, 0x4000
	s_add_i32 s43, s40, 0x6000
	s_add_i32 s47, s44, 0x6000
	s_waitcnt lgkmcnt(6)
	v_mfma_f32_16x16x32_bf16 v[126:129], v[176:179], v[212:215], v[126:129]
	ds_read_b128 v[228:231], v245 offset:8192
	s_waitcnt lgkmcnt(6)
	v_mfma_f32_16x16x32_bf16 v[122:125], v[180:183], v[212:215], v[122:125]
	ds_read_b128 v[232:235], v245 offset:10240
	s_waitcnt lgkmcnt(6)
	v_mfma_f32_16x16x32_bf16 v[118:121], v[184:187], v[212:215], v[118:121]
	s_mov_b32 m0, s40
	s_waitcnt lgkmcnt(5)
	v_mfma_f32_16x16x32_bf16 v[114:117], v[188:191], v[212:215], v[114:117]
	global_load_lds_dwordx4 v[144:145], off
	s_waitcnt lgkmcnt(4)
	v_mfma_f32_16x16x32_bf16 v[110:113], v[176:179], v[216:219], v[110:113]
	s_mov_b32 m0, s41
	v_lshl_add_u64 v[204:205], v[144:145], 0, s[4:5]
	v_mfma_f32_16x16x32_bf16 v[106:109], v[180:183], v[216:219], v[106:109]
	global_load_lds_dwordx4 v[204:205], off
	v_mfma_f32_16x16x32_bf16 v[102:105], v[184:187], v[216:219], v[102:105]
	s_mov_b32 m0, s42
	v_lshl_add_u64 v[204:205], v[144:145], 0, s[6:7]
	v_mfma_f32_16x16x32_bf16 v[98:101], v[188:191], v[216:219], v[98:101]
	global_load_lds_dwordx4 v[204:205], off
	s_waitcnt lgkmcnt(3)
	v_mfma_f32_16x16x32_bf16 v[94:97], v[176:179], v[220:223], v[94:97]
	ds_read_b128 v[236:239], v245 offset:12288
	v_mfma_f32_16x16x32_bf16 v[90:93], v[180:183], v[220:223], v[90:93]
	ds_read_b128 v[240:243], v245 offset:14336
	v_mfma_f32_16x16x32_bf16 v[86:89], v[184:187], v[220:223], v[86:89]
	s_mov_b32 m0, s43
	v_lshl_add_u64 v[204:205], v[144:145], 0, s[8:9]
	v_mfma_f32_16x16x32_bf16 v[82:85], v[188:191], v[220:223], v[82:85]
	global_load_lds_dwordx4 v[204:205], off
	s_waitcnt lgkmcnt(4)
	v_mfma_f32_16x16x32_bf16 v[78:81], v[176:179], v[224:227], v[78:81]
	s_mov_b32 m0, s44
	v_mfma_f32_16x16x32_bf16 v[74:77], v[180:183], v[224:227], v[74:77]
	global_load_lds_dwordx4 v[146:147], off
	v_mfma_f32_16x16x32_bf16 v[70:73], v[184:187], v[224:227], v[70:73]
	s_mov_b32 m0, s45
	v_lshl_add_u64 v[204:205], v[146:147], 0, s[4:5]
	v_mfma_f32_16x16x32_bf16 v[66:69], v[188:191], v[224:227], v[66:69]
	global_load_lds_dwordx4 v[204:205], off
	s_waitcnt lgkmcnt(3)
	v_mfma_f32_16x16x32_bf16 v[62:65], v[176:179], v[228:231], v[62:65]
	ds_read_b128 v[192:195], v246 offset:32768
	v_mfma_f32_16x16x32_bf16 v[58:61], v[180:183], v[228:231], v[58:61]
	ds_read_b128 v[196:199], v246 offset:34816
	v_mfma_f32_16x16x32_bf16 v[54:57], v[184:187], v[228:231], v[54:57]
	ds_read_b128 v[200:203], v246 offset:36864
	v_mfma_f32_16x16x32_bf16 v[50:53], v[188:191], v[228:231], v[50:53]
	ds_read_b128 v[208:211], v246 offset:38912
	s_waitcnt lgkmcnt(6)
	v_mfma_f32_16x16x32_bf16 v[46:49], v[176:179], v[232:235], v[46:49]
	ds_read_b128 v[212:215], v247
	v_mfma_f32_16x16x32_bf16 v[42:45], v[180:183], v[232:235], v[42:45]
	ds_read_b128 v[216:219], v247 offset:2048
	v_mfma_f32_16x16x32_bf16 v[34:37], v[184:187], v[232:235], v[34:37]
	s_mov_b32 m0, s46
	v_lshl_add_u64 v[204:205], v[146:147], 0, s[6:7]
	v_mfma_f32_16x16x32_bf16 v[30:33], v[188:191], v[232:235], v[30:33]
	global_load_lds_dwordx4 v[204:205], off
	s_mov_b32 m0, s47
	v_lshl_add_u64 v[204:205], v[146:147], 0, s[8:9]
	global_load_lds_dwordx4 v[204:205], off
	v_lshl_add_u64 v[144:145], v[144:145], 0, s[10:11]
	v_lshl_add_u64 v[146:147], v[146:147], 0, s[10:11]
	s_waitcnt lgkmcnt(7)
	v_mfma_f32_16x16x32_bf16 v[26:29], v[176:179], v[236:239], v[26:29]
	ds_read_b128 v[220:223], v247 offset:4096
	v_mfma_f32_16x16x32_bf16 v[22:25], v[180:183], v[236:239], v[22:25]
	ds_read_b128 v[224:227], v247 offset:6144
	v_mfma_f32_16x16x32_bf16 v[18:21], v[184:187], v[236:239], v[18:21]
	v_mfma_f32_16x16x32_bf16 v[14:17], v[188:191], v[236:239], v[14:17]
	s_waitcnt lgkmcnt(8)
	v_mfma_f32_16x16x32_bf16 v[10:13], v[176:179], v[240:243], v[10:13]
	v_mfma_f32_16x16x32_bf16 v[6:9], v[180:183], v[240:243], v[6:9]
	v_mfma_f32_16x16x32_bf16 v[2:5], v[184:187], v[240:243], v[2:5]
	v_mfma_f32_16x16x32_bf16 v[38:41], v[188:191], v[240:243], v[38:41]
	s_waitcnt lgkmcnt(3)
	v_mfma_f32_16x16x32_bf16 v[126:129], v[192:195], v[212:215], v[126:129]
	ds_read_b128 v[228:231], v247 offset:8192
	v_mfma_f32_16x16x32_bf16 v[122:125], v[196:199], v[212:215], v[122:125]
	ds_read_b128 v[232:235], v247 offset:10240
	v_mfma_f32_16x16x32_bf16 v[118:121], v[200:203], v[212:215], v[118:121]
	v_mfma_f32_16x16x32_bf16 v[114:117], v[208:211], v[212:215], v[114:117]
	s_waitcnt lgkmcnt(4)
	v_mfma_f32_16x16x32_bf16 v[110:113], v[192:195], v[216:219], v[110:113]
	v_mfma_f32_16x16x32_bf16 v[106:109], v[196:199], v[216:219], v[106:109]
	v_mfma_f32_16x16x32_bf16 v[102:105], v[200:203], v[216:219], v[102:105]
	v_mfma_f32_16x16x32_bf16 v[98:101], v[208:211], v[216:219], v[98:101]
	s_waitcnt lgkmcnt(3)
	v_mfma_f32_16x16x32_bf16 v[94:97], v[192:195], v[220:223], v[94:97]
	ds_read_b128 v[236:239], v247 offset:12288
	v_mfma_f32_16x16x32_bf16 v[90:93], v[196:199], v[220:223], v[90:93]
	ds_read_b128 v[240:243], v247 offset:14336
	v_mfma_f32_16x16x32_bf16 v[86:89], v[200:203], v[220:223], v[86:89]
	v_mfma_f32_16x16x32_bf16 v[82:85], v[208:211], v[220:223], v[82:85]
	s_waitcnt lgkmcnt(4)
	v_mfma_f32_16x16x32_bf16 v[78:81], v[192:195], v[224:227], v[78:81]
	v_mfma_f32_16x16x32_bf16 v[74:77], v[196:199], v[224:227], v[74:77]
	v_mfma_f32_16x16x32_bf16 v[70:73], v[200:203], v[224:227], v[70:73]
	v_mfma_f32_16x16x32_bf16 v[66:69], v[208:211], v[224:227], v[66:69]
	s_add_i32 s21, s21, 0x10000
; #define GLDS_STAGE(st, kt_) do { \
;         _Pragma("unroll") for (int i_ = 0; i_ < FI; ++i_) { \
;             glds16(ap + (size_t)(32 * i_) * lda + (kt_) * 64, l3a + (st) + tid * 16 + i_ * 4096); \
;             glds16(bp + (size_t)(32 * i_) * ldb + (kt_) * 64, l3a + (st) + OPB + tid * 16 + i_ * 4096); } } while (0)
; #define GLDS_STAGE(st, kt_) do { \
;         _Pragma("unroll") for (int i_ = 0; i_ < 4; ++i_) { \
;             glds16(ap + (size_t)(64 * i_) * lda + (kt_) * 64, l3a + (st) + tid * 16 + i_ * 8192); \
;             glds16(bp + (size_t)(64 * i_) * ldb + (kt_) * 64, l3a + (st) + 32768 + tid * 16 + i_ * 8192); } } while (0)
; template <class Epi>
; DEV void gemm256_tile(const bf16_t* __restrict__ A, int lda, const bf16_t* __restrict__ Bt, int ldb, int K, unsigned char* lds, const Epi& epi) {
;     ...
;     GLDS_STAGE(0, 0);
;     const int aoff = (wr * 128 + fr) * 128, boff = 32768 + (wc * 64 + fr) * 128, sw = fr & 7;
;     for (int kt = 0; kt < nk; ++kt) {
;         const int cur = (kt & 1) * 65536;
;         asm volatile("s_waitcnt vmcnt(0)" ::: "memory");
;         __syncthreads();
;         if (kt + 1 < nk) GLDS_STAGE(cur ^ 65536, kt + 1);
; #pragma unroll
;         for (int kh = 0; kh < 2; ++kh) {
;             bf16x8 bfr[4];
;             const int ch = ((kh * 4 + fq) ^ sw) << 4;
; #pragma unroll
;             for (int i = 0; i < 4; ++i) bfr[i] = *(const bf16x8*)(lds + cur + boff + i * 2048 + ch);
; #pragma unroll
;             for (int mh = 0; mh < 2; ++mh) {
;                 bf16x8 af[4];
; #pragma unroll
;                 for (int i = 0; i < 4; ++i) af[i] = *(const bf16x8*)(lds + cur + aoff + (mh * 4 + i) * 2048 + ch);
; #pragma unroll
;                 for (int mi = 0; mi < 4; ++mi)
; #pragma unroll
;                     for (int ni = 0; ni < 4; ++ni) acc[mh * 4 + mi][ni] = __builtin_amdgcn_mfma_f32_16x16x32_bf16(bfr[ni], af[mi], acc[mh * 4 + mi][ni], 0, 0, 0);
;             }
;         }
.Lg256r_a:
	s_and_b32 s48, s21, 0x10000
	s_xor_b32 s49, s48, 0x10000
	v_add_u32_e32 v206, s49, v142
	v_add_u32_e32 v207, s49, v156
	s_waitcnt vmcnt(0) lgkmcnt(0)
	s_barrier
	v_or_b32_e32 v248, s48, v175
	v_add_u32_e32 v249, s48, v157
	v_add_u32_e32 v244, v248, v174
	v_add_u32_e32 v245, v249, v174
	v_add_u32_e32 v246, v248, v155
	v_add_u32_e32 v247, v249, v155
	ds_read_b128 v[176:179], v244 offset:32768
	ds_read_b128 v[212:215], v245
	ds_read_b128 v[180:183], v244 offset:34816
	ds_read_b128 v[184:187], v244 offset:36864
	ds_read_b128 v[188:191], v244 offset:38912
	ds_read_b128 v[216:219], v245 offset:2048
	ds_read_b128 v[220:223], v245 offset:4096
	ds_read_b128 v[224:227], v245 offset:6144
	v_readfirstlane_b32 s40, v206
	v_readfirstlane_b32 s44, v207
	s_nop 0
	s_add_i32 s41, s40, 0x2000
	s_add_i32 s45, s44, 0x2000
	s_add_i32 s42, s40, 0x4000
	s_add_i32 s46, s44, 0x4000
	s_add_i32 s43, s40, 0x6000
	s_add_i32 s47, s44, 0x6000
	v_mfma_f32_16x16x32_bf16 v[62:65], v[192:195], v[228:231], v[62:65]
	s_mov_b32 m0, s40
	v_mfma_f32_16x16x32_bf16 v[58:61], v[196:199], v[228:231], v[58:61]
	global_load_lds_dwordx4 v[144:145], off
	v_mfma_f32_16x16x32_bf16 v[54:57], v[200:203], v[228:231], v[54:57]
	s_mov_b32 m0, s41
	v_lshl_add_u64 v[204:205], v[144:145], 0, s[4:5]
	v_mfma_f32_16x16x32_bf16 v[50:53], v[208:211], v[228:231], v[50:53]
	global_load_lds_dwordx4 v[204:205], off
	v_mfma_f32_16x16x32_bf16 v[46:49], v[192:195], v[232:235], v[46:49]
	s_mov_b32 m0, s42
	v_lshl_add_u64 v[204:205], v[144:145], 0, s[6:7]
	v_mfma_f32_16x16x32_bf16 v[42:45], v[196:199], v[232:235], v[42:45]
	global_load_lds_dwordx4 v[204:205], off
	v_mfma_f32_16x16x32_bf16 v[34:37], v[200:203], v[232:235], v[34:37]
	s_mov_b32 m0, s43
	v_lshl_add_u64 v[204:205], v[144:145], 0, s[8:9]
	v_mfma_f32_16x16x32_bf16 v[30:33], v[208:211], v[232:235], v[30:33]
	global_load_lds_dwordx4 v[204:205], off
	v_mfma_f32_16x16x32_bf16 v[26:29], v[192:195], v[236:239], v[26:29]
	s_mov_b32 m0, s44
	v_mfma_f32_16x16x32_bf16 v[22:25], v[196:199], v[236:239], v[22:25]
	global_load_lds_dwordx4 v[146:147], off
	v_mfma_f32_16x16x32_bf16 v[18:21], v[200:203], v[236:239], v[18:21]
	s_mov_b32 m0, s45
	v_lshl_add_u64 v[204:205], v[146:147], 0, s[4:5]
	v_mfma_f32_16x16x32_bf16 v[14:17], v[208:211], v[236:239], v[14:17]
	global_load_lds_dwordx4 v[204:205], off
	v_mfma_f32_16x16x32_bf16 v[10:13], v[192:195], v[240:243], v[10:13]
	s_mov_b32 m0, s46
	v_lshl_add_u64 v[204:205], v[146:147], 0, s[6:7]
	v_mfma_f32_16x16x32_bf16 v[6:9], v[196:199], v[240:243], v[6:9]
	global_load_lds_dwordx4 v[204:205], off
	v_mfma_f32_16x16x32_bf16 v[2:5], v[200:203], v[240:243], v[2:5]
	s_mov_b32 m0, s47
	v_lshl_add_u64 v[204:205], v[146:147], 0, s[8:9]
	v_mfma_f32_16x16x32_bf16 v[38:41], v[208:211], v[240:243], v[38:41]
	global_load_lds_dwordx4 v[204:205], off
	v_lshl_add_u64 v[144:145], v[144:145], 0, s[10:11]
	v_lshl_add_u64 v[146:147], v[146:147], 0, s[10:11]
	s_waitcnt lgkmcnt(6)
	v_mfma_f32_16x16x32_bf16 v[126:129], v[176:179], v[212:215], v[126:129]
	ds_read_b128 v[228:231], v245 offset:8192
	s_waitcnt lgkmcnt(6)
	v_mfma_f32_16x16x32_bf16 v[122:125], v[180:183], v[212:215], v[122:125]
	ds_read_b128 v[232:235], v245 offset:10240
	s_waitcnt lgkmcnt(6)
	v_mfma_f32_16x16x32_bf16 v[118:121], v[184:187], v[212:215], v[118:121]
	s_waitcnt lgkmcnt(5)
	v_mfma_f32_16x16x32_bf16 v[114:117], v[188:191], v[212:215], v[114:117]
	s_waitcnt lgkmcnt(4)
	v_mfma_f32_16x16x32_bf16 v[110:113], v[176:179], v[216:219], v[110:113]
	v_mfma_f32_16x16x32_bf16 v[106:109], v[180:183], v[216:219], v[106:109]
	v_mfma_f32_16x16x32_bf16 v[102:105], v[184:187], v[216:219], v[102:105]
	v_mfma_f32_16x16x32_bf16 v[98:101], v[188:191], v[216:219], v[98:101]
	s_waitcnt lgkmcnt(3)
	v_mfma_f32_16x16x32_bf16 v[94:97], v[176:179], v[220:223], v[94:97]
	ds_read_b128 v[236:239], v245 offset:12288
	v_mfma_f32_16x16x32_bf16 v[90:93], v[180:183], v[220:223], v[90:93]
	ds_read_b128 v[240:243], v245 offset:14336
	v_mfma_f32_16x16x32_bf16 v[86:89], v[184:187], v[220:223], v[86:89]
	v_mfma_f32_16x16x32_bf16 v[82:85], v[188:191], v[220:223], v[82:85]
	s_waitcnt lgkmcnt(4)
	v_mfma_f32_16x16x32_bf16 v[78:81], v[176:179], v[224:227], v[78:81]
	v_mfma_f32_16x16x32_bf16 v[74:77], v[180:183], v[224:227], v[74:77]
	v_mfma_f32_16x16x32_bf16 v[70:73], v[184:187], v[224:227], v[70:73]
	v_mfma_f32_16x16x32_bf16 v[66:69], v[188:191], v[224:227], v[66:69]
	s_waitcnt lgkmcnt(3)
	v_mfma_f32_16x16x32_bf16 v[62:65], v[176:179], v[228:231], v[62:65]
	ds_read_b128 v[192:195], v246 offset:32768
	v_mfma_f32_16x16x32_bf16 v[58:61], v[180:183], v[228:231], v[58:61]
	ds_read_b128 v[196:199], v246 offset:34816
	v_mfma_f32_16x16x32_bf16 v[54:57], v[184:187], v[228:231], v[54:57]
	ds_read_b128 v[200:203], v246 offset:36864
	v_mfma_f32_16x16x32_bf16 v[50:53], v[188:191], v[228:231], v[50:53]
	ds_read_b128 v[208:211], v246 offset:38912
	s_waitcnt lgkmcnt(6)
	v_mfma_f32_16x16x32_bf16 v[46:49], v[176:179], v[232:235], v[46:49]
	ds_read_b128 v[212:215], v247
	v_mfma_f32_16x16x32_bf16 v[42:45], v[180:183], v[232:235], v[42:45]
	ds_read_b128 v[216:219], v247 offset:2048
	v_mfma_f32_16x16x32_bf16 v[34:37], v[184:187], v[232:235], v[34:37]
	v_mfma_f32_16x16x32_bf16 v[30:33], v[188:191], v[232:235], v[30:33]
	s_waitcnt lgkmcnt(7)
	v_mfma_f32_16x16x32_bf16 v[26:29], v[176:179], v[236:239], v[26:29]
	ds_read_b128 v[220:223], v247 offset:4096
	v_mfma_f32_16x16x32_bf16 v[22:25], v[180:183], v[236:239], v[22:25]
	ds_read_b128 v[224:227], v247 offset:6144
	v_mfma_f32_16x16x32_bf16 v[18:21], v[184:187], v[236:239], v[18:21]
	v_mfma_f32_16x16x32_bf16 v[14:17], v[188:191], v[236:239], v[14:17]
	s_waitcnt lgkmcnt(8)
; #define GLDS_STAGE(st, kt_) do { \
;         _Pragma("unroll") for (int i_ = 0; i_ < FI; ++i_) { \
;             glds16(ap + (size_t)(32 * i_) * lda + (kt_) * 64, l3a + (st) + tid * 16 + i_ * 4096); \
;             glds16(bp + (size_t)(32 * i_) * ldb + (kt_) * 64, l3a + (st) + OPB + tid * 16 + i_ * 4096); } } while (0)
; #define GLDS_STAGE(st, kt_) do { \
;         _Pragma("unroll") for (int i_ = 0; i_ < 4; ++i_) { \
;             glds16(ap + (size_t)(64 * i_) * lda + (kt_) * 64, l3a + (st) + tid * 16 + i_ * 8192); \
;             glds16(bp + (size_t)(64 * i_) * ldb + (kt_) * 64, l3a + (st) + 32768 + tid * 16 + i_ * 8192); } } while (0)
; template <class Epi>
; DEV void gemm256_tile(const bf16_t* __restrict__ A, int lda, const bf16_t* __restrict__ Bt, int ldb, int K, unsigned char* lds, const Epi& epi) {
;     ...
;     for (int kt = 0; kt < nk; ++kt) {
;         const int cur = (kt & 1) * 65536;
;         asm volatile("s_waitcnt vmcnt(0)" ::: "memory");
;         __syncthreads();
;         if (kt + 1 < nk) GLDS_STAGE(cur ^ 65536, kt + 1);
; #pragma unroll
;         for (int kh = 0; kh < 2; ++kh) {
;             bf16x8 bfr[4];
;             const int ch = ((kh * 4 + fq) ^ sw) << 4;
; #pragma unroll
;             for (int i = 0; i < 4; ++i) bfr[i] = *(const bf16x8*)(lds + cur + boff + i * 2048 + ch);
; #pragma unroll
;             for (int mh = 0; mh < 2; ++mh) {
;                 bf16x8 af[4];
; #pragma unroll
;                 for (int i = 0; i < 4; ++i) af[i] = *(const bf16x8*)(lds + cur + aoff + (mh * 4 + i) * 2048 + ch);
; #pragma unroll
;                 for (int mi = 0; mi < 4; ++mi)
; #pragma unroll
;                     for (int ni = 0; ni < 4; ++ni) acc[mh * 4 + mi][ni] = __builtin_amdgcn_mfma_f32_16x16x32_bf16(bfr[ni], af[mi], acc[mh * 4 + mi][ni], 0, 0, 0);
;             }
;         }
	v_mfma_f32_16x16x32_bf16 v[10:13], v[176:179], v[240:243], v[10:13]
	v_mfma_f32_16x16x32_bf16 v[6:9], v[180:183], v[240:243], v[6:9]
	v_mfma_f32_16x16x32_bf16 v[2:5], v[184:187], v[240:243], v[2:5]
	v_mfma_f32_16x16x32_bf16 v[38:41], v[188:191], v[240:243], v[38:41]
	s_waitcnt lgkmcnt(3)
	v_mfma_f32_16x16x32_bf16 v[126:129], v[192:195], v[212:215], v[126:129]
	ds_read_b128 v[228:231], v247 offset:8192
	v_mfma_f32_16x16x32_bf16 v[122:125], v[196:199], v[212:215], v[122:125]
	ds_read_b128 v[232:235], v247 offset:10240
	v_mfma_f32_16x16x32_bf16 v[118:121], v[200:203], v[212:215], v[118:121]
	v_mfma_f32_16x16x32_bf16 v[114:117], v[208:211], v[212:215], v[114:117]
	s_waitcnt lgkmcnt(4)
	v_mfma_f32_16x16x32_bf16 v[110:113], v[192:195], v[216:219], v[110:113]
	v_mfma_f32_16x16x32_bf16 v[106:109], v[196:199], v[216:219], v[106:109]
	v_mfma_f32_16x16x32_bf16 v[102:105], v[200:203], v[216:219], v[102:105]
	v_mfma_f32_16x16x32_bf16 v[98:101], v[208:211], v[216:219], v[98:101]
	s_waitcnt lgkmcnt(3)
	v_mfma_f32_16x16x32_bf16 v[94:97], v[192:195], v[220:223], v[94:97]
	ds_read_b128 v[236:239], v247 offset:12288
	v_mfma_f32_16x16x32_bf16 v[90:93], v[196:199], v[220:223], v[90:93]
	ds_read_b128 v[240:243], v247 offset:14336
	v_mfma_f32_16x16x32_bf16 v[86:89], v[200:203], v[220:223], v[86:89]
	v_mfma_f32_16x16x32_bf16 v[82:85], v[208:211], v[220:223], v[82:85]
	s_waitcnt lgkmcnt(4)
	v_mfma_f32_16x16x32_bf16 v[78:81], v[192:195], v[224:227], v[78:81]
	v_mfma_f32_16x16x32_bf16 v[74:77], v[196:199], v[224:227], v[74:77]
	v_mfma_f32_16x16x32_bf16 v[70:73], v[200:203], v[224:227], v[70:73]
	v_mfma_f32_16x16x32_bf16 v[66:69], v[208:211], v[224:227], v[66:69]
	s_add_i32 s21, s21, 0x10000
	s_cmp_eq_u32 s21, 0x1f0000
	s_cbranch_scc0 .Lg256r_a
	s_waitcnt lgkmcnt(0)
	v_mfma_f32_16x16x32_bf16 v[62:65], v[192:195], v[228:231], v[62:65]
	v_mfma_f32_16x16x32_bf16 v[58:61], v[196:199], v[228:231], v[58:61]
	v_mfma_f32_16x16x32_bf16 v[54:57], v[200:203], v[228:231], v[54:57]
	v_mfma_f32_16x16x32_bf16 v[50:53], v[208:211], v[228:231], v[50:53]
	v_mfma_f32_16x16x32_bf16 v[46:49], v[192:195], v[232:235], v[46:49]
	v_mfma_f32_16x16x32_bf16 v[42:45], v[196:199], v[232:235], v[42:45]
	v_mfma_f32_16x16x32_bf16 v[34:37], v[200:203], v[232:235], v[34:37]
	v_mfma_f32_16x16x32_bf16 v[30:33], v[208:211], v[232:235], v[30:33]
	v_mfma_f32_16x16x32_bf16 v[26:29], v[192:195], v[236:239], v[26:29]
	v_mfma_f32_16x16x32_bf16 v[22:25], v[196:199], v[236:239], v[22:25]
	v_mfma_f32_16x16x32_bf16 v[18:21], v[200:203], v[236:239], v[18:21]
	v_mfma_f32_16x16x32_bf16 v[14:17], v[208:211], v[236:239], v[14:17]
	v_mfma_f32_16x16x32_bf16 v[10:13], v[192:195], v[240:243], v[10:13]
	v_mfma_f32_16x16x32_bf16 v[6:9], v[196:199], v[240:243], v[6:9]
	v_mfma_f32_16x16x32_bf16 v[2:5], v[200:203], v[240:243], v[2:5]
	v_mfma_f32_16x16x32_bf16 v[38:41], v[208:211], v[240:243], v[38:41]
	v_or_b32_e32 v156, 0x18000, v175
	v_add_u32_e32 v157, 0x10000, v157
	v_add_u32_e32 v186, v156, v174
	v_add_u32_e32 v194, v157, v174
	s_waitcnt vmcnt(0)
	s_barrier
	ds_read_b128 v[144:147], v186
	ds_read_b128 v[178:181], v186 offset:2048
	ds_read_b128 v[174:177], v194
	ds_read_b128 v[182:185], v186 offset:4096
	ds_read_b128 v[186:189], v186 offset:6144
	s_waitcnt lgkmcnt(2)
	v_mfma_f32_16x16x32_bf16 v[126:129], v[144:147], v[174:177], v[126:129]
	s_sext_i32_i16 s20, s20
	s_lshl_b32 s20, s20, 8
	s_ashr_i32 s21, s20, 31
	v_mfma_f32_16x16x32_bf16 v[122:125], v[178:181], v[174:177], v[122:125]
	s_waitcnt lgkmcnt(1)
	v_mfma_f32_16x16x32_bf16 v[118:121], v[182:185], v[174:177], v[118:121]
	s_waitcnt lgkmcnt(0)
	v_mfma_f32_16x16x32_bf16 v[114:117], v[186:189], v[174:177], v[114:117]
	ds_read_b128 v[174:177], v194 offset:2048
	s_waitcnt lgkmcnt(0)
	v_mfma_f32_16x16x32_bf16 v[110:113], v[144:147], v[174:177], v[110:113]
	v_mfma_f32_16x16x32_bf16 v[106:109], v[178:181], v[174:177], v[106:109]
	v_mfma_f32_16x16x32_bf16 v[102:105], v[182:185], v[174:177], v[102:105]
	v_mfma_f32_16x16x32_bf16 v[98:101], v[186:189], v[174:177], v[98:101]
	ds_read_b128 v[174:177], v194 offset:4096
	s_waitcnt lgkmcnt(0)
	v_mfma_f32_16x16x32_bf16 v[94:97], v[144:147], v[174:177], v[94:97]
	v_mfma_f32_16x16x32_bf16 v[90:93], v[178:181], v[174:177], v[90:93]
	v_mfma_f32_16x16x32_bf16 v[86:89], v[182:185], v[174:177], v[86:89]
	v_mfma_f32_16x16x32_bf16 v[82:85], v[186:189], v[174:177], v[82:85]
	ds_read_b128 v[174:177], v194 offset:6144
	s_waitcnt lgkmcnt(0)
	v_mfma_f32_16x16x32_bf16 v[78:81], v[144:147], v[174:177], v[78:81]
	v_mfma_f32_16x16x32_bf16 v[74:77], v[178:181], v[174:177], v[74:77]
	v_mfma_f32_16x16x32_bf16 v[70:73], v[182:185], v[174:177], v[70:73]
	v_mfma_f32_16x16x32_bf16 v[66:69], v[186:189], v[174:177], v[66:69]
	ds_read_b128 v[174:177], v194 offset:8192
	ds_read_b128 v[190:193], v194 offset:10240
	s_waitcnt lgkmcnt(1)
	v_mfma_f32_16x16x32_bf16 v[62:65], v[144:147], v[174:177], v[62:65]
	v_mfma_f32_16x16x32_bf16 v[58:61], v[178:181], v[174:177], v[58:61]
	v_mfma_f32_16x16x32_bf16 v[54:57], v[182:185], v[174:177], v[54:57]
	v_mfma_f32_16x16x32_bf16 v[50:53], v[186:189], v[174:177], v[50:53]
	ds_read_b128 v[174:177], v194 offset:12288
	s_waitcnt lgkmcnt(1)
	v_mfma_f32_16x16x32_bf16 v[46:49], v[144:147], v[190:193], v[46:49]
	v_mfma_f32_16x16x32_bf16 v[42:45], v[178:181], v[190:193], v[42:45]
	v_mfma_f32_16x16x32_bf16 v[34:37], v[182:185], v[190:193], v[34:37]
	v_mfma_f32_16x16x32_bf16 v[30:33], v[186:189], v[190:193], v[30:33]
	ds_read_b128 v[190:193], v194 offset:14336
	s_waitcnt lgkmcnt(1)
; DEV unsigned cvt_pk_bf16(float lo, float hi) { const f32x2_t v = {lo, hi}; const bf16x2_t b = __builtin_convertvector(v, bf16x2_t); return __builtin_bit_cast(unsigned, b); }
; template <class Epi>
; DEV void gemm256_tile(const bf16_t* __restrict__ A, int lda, const bf16_t* __restrict__ Bt, int ldb, int K, unsigned char* lds, const Epi& epi) {
;     ...
; #pragma unroll
;         for (int kh = 0; kh < 2; ++kh) {
;             bf16x8 bfr[4];
;             const int ch = ((kh * 4 + fq) ^ sw) << 4;
; #pragma unroll
;             for (int i = 0; i < 4; ++i) bfr[i] = *(const bf16x8*)(lds + cur + boff + i * 2048 + ch);
; #pragma unroll
;             for (int mh = 0; mh < 2; ++mh) {
;                 bf16x8 af[4];
; #pragma unroll
;                 for (int i = 0; i < 4; ++i) af[i] = *(const bf16x8*)(lds + cur + aoff + (mh * 4 + i) * 2048 + ch);
; #pragma unroll
;                 for (int mi = 0; mi < 4; ++mi)
; #pragma unroll
;                     for (int ni = 0; ni < 4; ++ni) acc[mh * 4 + mi][ni] = __builtin_amdgcn_mfma_f32_16x16x32_bf16(bfr[ni], af[mi], acc[mh * 4 + mi][ni], 0, 0, 0);
;             }
;     ...
; #pragma unroll
;         for (int mi = 0; mi < 8; ++mi)
; #pragma unroll
;             for (int ni = 0; ni < 4; ++ni) {
;                 const int row = wr * 128 + mi * 16 + fr, col = wc * 64 + ni * 16 + fq * 4;
;                 const f32x4 v = epi.xform(row, col, acc[mi][ni]);
;                 uint2 w; w.x = cvt_pk_bf16(v[0], v[1]); w.y = cvt_pk_bf16(v[2], v[3]);
;                 *(uint2*)(lds + row * 512 + ((((col >> 3) ^ (row & 31)) << 4) | (((col >> 2) & 1) << 3))) = w;
	v_mfma_f32_16x16x32_bf16 v[194:197], v[144:147], v[174:177], v[26:29]
	s_nop 2
	v_add_u32_e32 v29, v156, v155
	ds_read_b128 v[198:201], v29
	ds_read_b128 v[202:205], v29 offset:2048
	ds_read_b128 v[206:209], v29 offset:4096
	ds_read_b128 v[210:213], v29 offset:6144
	v_add_u32_e32 v29, v157, v155
	v_mfma_f32_16x16x32_bf16 v[22:25], v[178:181], v[174:177], v[22:25]
	v_and_b32_e32 v28, 0xc0, v150
	v_lshl_or_b32 v153, v153, 2, v28
	v_lshlrev_b32_e32 v28, 3, v152
	v_mfma_f32_16x16x32_bf16 v[18:21], v[182:185], v[174:177], v[18:21]
	v_mad_i64_i32 v[26:27], s[22:23], s19, v149, v[172:173]
	v_lshl_add_u64 v[26:27], s[20:21], 1, v[26:27]
	v_mfma_f32_16x16x32_bf16 v[14:17], v[186:189], v[174:177], v[14:17]
	ds_read_b128 v[174:177], v29
	ds_read_b128 v[214:217], v29 offset:2048
	ds_read_b128 v[218:221], v29 offset:4096
	ds_read_b128 v[222:225], v29 offset:6144
	s_mov_b32 s19, 0
	s_waitcnt lgkmcnt(3)
	v_mfma_f32_16x16x32_bf16 v[126:129], v[198:201], v[174:177], v[126:129]
	v_mfma_f32_16x16x32_bf16 v[122:125], v[202:205], v[174:177], v[122:125]
	s_waitcnt lgkmcnt(1)
	v_mfma_f32_16x16x32_bf16 v[94:97], v[198:201], v[218:221], v[94:97]
	v_mfma_f32_16x16x32_bf16 v[10:13], v[144:147], v[190:193], v[10:13]
	ds_read_b128 v[144:147], v29 offset:8192
	ds_read_b128 v[226:229], v29 offset:10240
	ds_read_b128 v[230:233], v29 offset:12288
	ds_read_b128 v[234:237], v29 offset:14336
	v_lshlrev_b32_e32 v29, 9, v154
	v_and_or_b32 v152, v28, 8, v29
	v_mfma_f32_16x16x32_bf16 v[118:121], v[206:209], v[174:177], v[118:121]
	v_cvt_pk_bf16_f32 v28, v126, v127
	v_lshrrev_b32_e32 v126, 3, v153
	v_xor_b32_e32 v127, v126, v151
	v_mfma_f32_16x16x32_bf16 v[90:93], v[202:205], v[218:221], v[90:93]
	v_cvt_pk_bf16_f32 v29, v128, v129
	v_lshl_or_b32 v127, v127, 4, v152
	v_cvt_pk_bf16_f32 v122, v122, v123
	v_mfma_f32_16x16x32_bf16 v[114:117], v[210:213], v[174:177], v[114:117]
	v_cvt_pk_bf16_f32 v123, v124, v125
	v_bitop3_b32 v124, v126, v151, 2 bitop3:0x36
	v_cvt_pk_bf16_f32 v94, v94, v95
	v_mfma_f32_16x16x32_bf16 v[86:89], v[206:209], v[218:221], v[86:89]
	v_cvt_pk_bf16_f32 v95, v96, v97
	s_waitcnt lgkmcnt(0)
	s_barrier
; DEV unsigned cvt_pk_bf16(float lo, float hi) { const f32x2_t v = {lo, hi}; const bf16x2_t b = __builtin_convertvector(v, bf16x2_t); return __builtin_bit_cast(unsigned, b); }
; template <class Epi>
; DEV void gemm256_tile(const bf16_t* __restrict__ A, int lda, const bf16_t* __restrict__ Bt, int ldb, int K, unsigned char* lds, const Epi& epi) {
;     ...
; #pragma unroll
;         for (int mi = 0; mi < 8; ++mi)
; #pragma unroll
;             for (int ni = 0; ni < 4; ++ni) {
;                 const int row = wr * 128 + mi * 16 + fr, col = wc * 64 + ni * 16 + fq * 4;
;                 const f32x4 v = epi.xform(row, col, acc[mi][ni]);
;                 uint2 w; w.x = cvt_pk_bf16(v[0], v[1]); w.y = cvt_pk_bf16(v[2], v[3]);
;                 *(uint2*)(lds + row * 512 + ((((col >> 3) ^ (row & 31)) << 4) | (((col >> 2) & 1) << 3))) = w;
;             }
;         __syncthreads();
	v_mfma_f32_16x16x32_bf16 v[110:113], v[198:201], v[214:217], v[110:113]
	v_lshl_add_u32 v124, v124, 4, v152
	v_cvt_pk_bf16_f32 v118, v118, v119
	v_mfma_f32_16x16x32_bf16 v[82:85], v[210:213], v[218:221], v[82:85]
	v_cvt_pk_bf16_f32 v119, v120, v121
	v_bitop3_b32 v120, v126, v151, 4 bitop3:0x36
	ds_write2st64_b64 v127, v[28:29], v[94:95] offset1:32
	v_mfma_f32_16x16x32_bf16 v[106:109], v[202:205], v[214:217], v[106:109]
	v_cvt_pk_bf16_f32 v28, v90, v91
	v_cvt_pk_bf16_f32 v29, v92, v93
	v_lshl_add_u32 v120, v120, 4, v152
	v_mfma_f32_16x16x32_bf16 v[78:81], v[198:201], v[222:225], v[78:81]
	v_cvt_pk_bf16_f32 v114, v114, v115
	v_cvt_pk_bf16_f32 v115, v116, v117
	v_bitop3_b32 v116, v126, v151, 6 bitop3:0x36
	v_mfma_f32_16x16x32_bf16 v[102:105], v[206:209], v[214:217], v[102:105]
	ds_write2st64_b64 v124, v[122:123], v[28:29] offset1:32
	v_cvt_pk_bf16_f32 v28, v86, v87
	v_cvt_pk_bf16_f32 v29, v88, v89
	v_mfma_f32_16x16x32_bf16 v[74:77], v[202:205], v[222:225], v[74:77]
	v_lshl_add_u32 v116, v116, 4, v152
	v_or_b32_e32 v117, 16, v151
	v_cvt_pk_bf16_f32 v110, v110, v111
	v_mfma_f32_16x16x32_bf16 v[2:5], v[182:185], v[190:193], v[2:5]
	v_cvt_pk_bf16_f32 v111, v112, v113
	v_bitop3_b32 v112, v126, v151, 16 bitop3:0x1e
	ds_write2st64_b64 v120, v[118:119], v[28:29] offset1:32
	v_mfma_f32_16x16x32_bf16 v[98:101], v[210:213], v[214:217], v[98:101]
	v_cvt_pk_bf16_f32 v28, v82, v83
	v_cvt_pk_bf16_f32 v29, v84, v85
	v_lshl_or_b32 v112, v112, 4, v152
	v_mfma_f32_16x16x32_bf16 v[70:73], v[206:209], v[222:225], v[70:73]
	v_cvt_pk_bf16_f32 v106, v106, v107
	v_cvt_pk_bf16_f32 v107, v108, v109
	v_bitop3_b32 v108, v126, v117, 2 bitop3:0x36
	v_mfma_f32_16x16x32_bf16 v[66:69], v[210:213], v[222:225], v[66:69]
	ds_write2st64_b64 v116, v[114:115], v[28:29] offset1:32
	v_cvt_pk_bf16_f32 v28, v78, v79
	v_cvt_pk_bf16_f32 v29, v80, v81
	v_lshl_add_u32 v108, v108, 4, v152
	v_cvt_pk_bf16_f32 v102, v102, v103
	v_cvt_pk_bf16_f32 v103, v104, v105
	v_bitop3_b32 v104, v126, v117, 4 bitop3:0x36
	ds_write2st64_b64 v112, v[110:111], v[28:29] offset0:16 offset1:48
	v_cvt_pk_bf16_f32 v28, v74, v75
	v_cvt_pk_bf16_f32 v29, v76, v77
	v_lshl_add_u32 v104, v104, 4, v152
	v_cvt_pk_bf16_f32 v98, v98, v99
	v_cvt_pk_bf16_f32 v99, v100, v101
	v_bitop3_b32 v100, v126, v117, 6 bitop3:0x36
	ds_write2st64_b64 v108, v[106:107], v[28:29] offset0:16 offset1:48
	v_cvt_pk_bf16_f32 v28, v70, v71
	v_cvt_pk_bf16_f32 v29, v72, v73
	v_mfma_f32_16x16x32_bf16 v[34:37], v[206:209], v[226:229], v[34:37]
	v_lshl_add_u32 v100, v100, 4, v152
	ds_write2st64_b64 v104, v[102:103], v[28:29] offset0:16 offset1:48
	v_cvt_pk_bf16_f32 v28, v66, v67
	v_mfma_f32_16x16x32_bf16 v[2:5], v[206:209], v[234:237], v[2:5]
	v_cvt_pk_bf16_f32 v29, v68, v69
	ds_write2st64_b64 v100, v[98:99], v[28:29] offset0:16 offset1:48
	s_nop 1
	v_cvt_pk_bf16_f32 v34, v34, v35
	v_mfma_f32_16x16x32_bf16 v[38:41], v[186:189], v[190:193], v[38:41]
	v_cvt_pk_bf16_f32 v35, v36, v37
	s_nop 0
	v_cvt_pk_bf16_f32 v2, v2, v3
	v_cvt_pk_bf16_f32 v3, v4, v5
	v_mfma_f32_16x16x32_bf16 v[6:9], v[178:181], v[190:193], v[6:9]
	ds_write2st64_b64 v104, v[34:35], v[2:3] offset0:80 offset1:112
	v_mfma_f32_16x16x32_bf16 v[28:31], v[210:213], v[226:229], v[30:33]
	v_mfma_f32_16x16x32_bf16 v[2:5], v[210:213], v[234:237], v[38:41]
	v_mfma_f32_16x16x32_bf16 v[62:65], v[198:201], v[144:147], v[62:65]
	s_nop 5
	v_cvt_pk_bf16_f32 v32, v28, v29
	v_cvt_pk_bf16_f32 v33, v30, v31
	v_cvt_pk_bf16_f32 v2, v2, v3
	v_mfma_f32_16x16x32_bf16 v[58:61], v[202:205], v[144:147], v[58:61]
	v_cvt_pk_bf16_f32 v3, v4, v5
	v_cvt_pk_bf16_f32 v62, v62, v63
	v_cvt_pk_bf16_f32 v63, v64, v65
	v_mfma_f32_16x16x32_bf16 v[54:57], v[206:209], v[144:147], v[54:57]
	ds_write2st64_b64 v100, v[32:33], v[2:3] offset0:80 offset1:112
	s_nop 2
	v_cvt_pk_bf16_f32 v58, v58, v59
	v_cvt_pk_bf16_f32 v59, v60, v61
	v_mfma_f32_16x16x32_bf16 v[50:53], v[210:213], v[144:147], v[50:53]
	v_and_b32_e32 v2, 0x1f0, v142
	v_cvt_pk_bf16_f32 v54, v54, v55
	v_cvt_pk_bf16_f32 v55, v56, v57
	v_mfma_f32_16x16x32_bf16 v[46:49], v[198:201], v[226:229], v[46:49]
	v_mfma_f32_16x16x32_bf16 v[42:45], v[202:205], v[226:229], v[42:45]
	s_nop 2
	v_cvt_pk_bf16_f32 v50, v50, v51
	v_cvt_pk_bf16_f32 v51, v52, v53
	s_nop 1
	v_cvt_pk_bf16_f32 v46, v46, v47
	v_mfma_f32_16x16x32_bf16 v[28:31], v[198:201], v[230:233], v[194:197]
	v_cvt_pk_bf16_f32 v47, v48, v49
	v_cvt_pk_bf16_f32 v42, v42, v43
	v_cvt_pk_bf16_f32 v43, v44, v45
	v_mfma_f32_16x16x32_bf16 v[22:25], v[202:205], v[230:233], v[22:25]
	v_mfma_f32_16x16x32_bf16 v[18:21], v[206:209], v[230:233], v[18:21]
	s_nop 2
	v_cvt_pk_bf16_f32 v28, v28, v29
	v_cvt_pk_bf16_f32 v29, v30, v31
	s_nop 1
	v_cvt_pk_bf16_f32 v22, v22, v23
	v_mfma_f32_16x16x32_bf16 v[14:17], v[210:213], v[230:233], v[14:17]
	v_cvt_pk_bf16_f32 v23, v24, v25
	v_cvt_pk_bf16_f32 v18, v18, v19
	v_cvt_pk_bf16_f32 v19, v20, v21
	v_mfma_f32_16x16x32_bf16 v[10:13], v[198:201], v[234:237], v[10:13]
	ds_write2st64_b64 v127, v[62:63], v[28:29] offset0:64 offset1:96
	s_nop 2
	v_cvt_pk_bf16_f32 v14, v14, v15
	v_cvt_pk_bf16_f32 v15, v16, v17
	v_mfma_f32_16x16x32_bf16 v[6:9], v[202:205], v[234:237], v[6:9]
	ds_write2st64_b64 v124, v[58:59], v[22:23] offset0:64 offset1:96
	v_cvt_pk_bf16_f32 v10, v10, v11
	v_cvt_pk_bf16_f32 v11, v12, v13
	ds_write2st64_b64 v120, v[54:55], v[18:19] offset0:64 offset1:96
	ds_write2st64_b64 v116, v[50:51], v[14:15] offset0:64 offset1:96
	s_nop 2
	v_cvt_pk_bf16_f32 v6, v6, v7
	v_cvt_pk_bf16_f32 v7, v8, v9
	ds_write2st64_b64 v112, v[46:47], v[10:11] offset0:80 offset1:112
	ds_write2st64_b64 v108, v[42:43], v[6:7] offset0:80 offset1:112
	s_waitcnt lgkmcnt(0)
	s_barrier

; #define GLDS_STAGE(st, kt_) do { \
;         _Pragma("unroll") for (int i_ = 0; i_ < FI; ++i_) { \
;             glds16(ap + (size_t)(32 * i_) * lda + (kt_) * 64, l3a + (st) + tid * 16 + i_ * 4096); \
;             glds16(bp + (size_t)(32 * i_) * ldb + (kt_) * 64, l3a + (st) + OPB + tid * 16 + i_ * 4096); } } while (0)
; #define GLDS_STAGE(st, kt_) do { \
;         _Pragma("unroll") for (int i_ = 0; i_ < 4; ++i_) { \
;             glds16(ap + (size_t)(64 * i_) * lda + (kt_) * 64, l3a + (st) + tid * 16 + i_ * 8192); \
;             glds16(bp + (size_t)(64 * i_) * ldb + (kt_) * 64, l3a + (st) + 32768 + tid * 16 + i_ * 8192); } } while (0)
; template <class Epi>
; DEV void gemm256_tile(const bf16_t* __restrict__ A, int lda, const bf16_t* __restrict__ Bt, int ldb, int K, unsigned char* lds, const Epi& epi) {
;     ...
;     GLDS_STAGE(0, 0);
;     const int aoff = (wr * 128 + fr) * 128, boff = 32768 + (wc * 64 + fr) * 128, sw = fr & 7;
;     for (int kt = 0; kt < nk; ++kt) {
;         const int cur = (kt & 1) * 65536;
;         asm volatile("s_waitcnt vmcnt(0)" ::: "memory");
;         __syncthreads();
;         if (kt + 1 < nk) GLDS_STAGE(cur ^ 65536, kt + 1);
; #pragma unroll
;         for (int kh = 0; kh < 2; ++kh) {
;             bf16x8 bfr[4];
;             const int ch = ((kh * 4 + fq) ^ sw) << 4;
; #pragma unroll
;             for (int i = 0; i < 4; ++i) bfr[i] = *(const bf16x8*)(lds + cur + boff + i * 2048 + ch);
; #pragma unroll
;             for (int mh = 0; mh < 2; ++mh) {
;                 bf16x8 af[4];
; #pragma unroll
;                 for (int i = 0; i < 4; ++i) af[i] = *(const bf16x8*)(lds + cur + aoff + (mh * 4 + i) * 2048 + ch);
; #pragma unroll
;                 for (int mi = 0; mi < 4; ++mi)
; #pragma unroll
;                     for (int ni = 0; ni < 4; ++ni) acc[mh * 4 + mi][ni] = __builtin_amdgcn_mfma_f32_16x16x32_bf16(bfr[ni], af[mi], acc[mh * 4 + mi][ni], 0, 0, 0);
;             }
;         }
.LBB0_1003:
	s_and_b32 s48, s25, 0x10000
	s_xor_b32 s49, s48, 0x10000
	v_add_u32_e32 v206, s49, v136
	v_add_u32_e32 v207, s49, v150
	s_waitcnt vmcnt(0) lgkmcnt(0)
	s_barrier
	v_or_b32_e32 v248, s48, v151
	v_add_u32_e32 v249, s48, v148
	v_add_u32_e32 v244, v248, v149
	v_add_u32_e32 v245, v249, v149
	v_add_u32_e32 v246, v248, v147
	v_add_u32_e32 v247, v249, v147
	ds_read_b128 v[152:155], v244 offset:32768
	ds_read_b128 v[212:215], v245
	ds_read_b128 v[176:179], v244 offset:34816
	ds_read_b128 v[180:183], v244 offset:36864
	ds_read_b128 v[184:187], v244 offset:38912
	ds_read_b128 v[216:219], v245 offset:2048
	ds_read_b128 v[220:223], v245 offset:4096
	ds_read_b128 v[224:227], v245 offset:6144
	v_readfirstlane_b32 s40, v206
	v_readfirstlane_b32 s44, v207
	s_nop 0
	s_add_i32 s41, s40, 0x2000
	s_add_i32 s45, s44, 0x2000
	s_add_i32 s42, s40, 0x4000
	s_add_i32 s46, s44, 0x4000
	s_add_i32 s43, s40, 0x6000
	s_add_i32 s47, s44, 0x6000
	s_waitcnt lgkmcnt(6)
	v_mfma_f32_16x16x32_bf16 v[126:129], v[152:155], v[212:215], v[126:129]
	ds_read_b128 v[228:231], v245 offset:8192
	s_waitcnt lgkmcnt(6)
	v_mfma_f32_16x16x32_bf16 v[122:125], v[176:179], v[212:215], v[122:125]
	ds_read_b128 v[232:235], v245 offset:10240
	s_waitcnt lgkmcnt(6)
	v_mfma_f32_16x16x32_bf16 v[118:121], v[180:183], v[212:215], v[118:121]
	s_mov_b32 m0, s40
	s_waitcnt lgkmcnt(5)
	v_mfma_f32_16x16x32_bf16 v[114:117], v[184:187], v[212:215], v[114:117]
	global_load_lds_dwordx4 v[138:139], off
	s_waitcnt lgkmcnt(4)
	v_mfma_f32_16x16x32_bf16 v[110:113], v[152:155], v[216:219], v[110:113]
	s_mov_b32 m0, s41
	v_lshl_add_u64 v[204:205], v[138:139], 0, s[6:7]
	v_mfma_f32_16x16x32_bf16 v[106:109], v[176:179], v[216:219], v[106:109]
	global_load_lds_dwordx4 v[204:205], off
	v_mfma_f32_16x16x32_bf16 v[102:105], v[180:183], v[216:219], v[102:105]
	s_mov_b32 m0, s42
	v_lshl_add_u64 v[204:205], v[138:139], 0, s[8:9]
	v_mfma_f32_16x16x32_bf16 v[98:101], v[184:187], v[216:219], v[98:101]
	global_load_lds_dwordx4 v[204:205], off
	s_waitcnt lgkmcnt(3)
	v_mfma_f32_16x16x32_bf16 v[94:97], v[152:155], v[220:223], v[94:97]
	ds_read_b128 v[236:239], v245 offset:12288
	v_mfma_f32_16x16x32_bf16 v[90:93], v[176:179], v[220:223], v[90:93]
	ds_read_b128 v[240:243], v245 offset:14336
	v_mfma_f32_16x16x32_bf16 v[86:89], v[180:183], v[220:223], v[86:89]
	s_mov_b32 m0, s43
	v_lshl_add_u64 v[204:205], v[138:139], 0, s[10:11]
	v_mfma_f32_16x16x32_bf16 v[82:85], v[184:187], v[220:223], v[82:85]
	global_load_lds_dwordx4 v[204:205], off
	s_waitcnt lgkmcnt(4)
	v_mfma_f32_16x16x32_bf16 v[78:81], v[152:155], v[224:227], v[78:81]
	s_mov_b32 m0, s44
	v_mfma_f32_16x16x32_bf16 v[74:77], v[176:179], v[224:227], v[74:77]
	global_load_lds_dwordx4 v[140:141], off
	v_mfma_f32_16x16x32_bf16 v[70:73], v[180:183], v[224:227], v[70:73]
	s_mov_b32 m0, s45
	v_lshl_add_u64 v[204:205], v[140:141], 0, s[6:7]
	v_mfma_f32_16x16x32_bf16 v[66:69], v[184:187], v[224:227], v[66:69]
	global_load_lds_dwordx4 v[204:205], off
	s_waitcnt lgkmcnt(3)
	v_mfma_f32_16x16x32_bf16 v[62:65], v[152:155], v[228:231], v[62:65]
	ds_read_b128 v[188:191], v246 offset:32768
	v_mfma_f32_16x16x32_bf16 v[58:61], v[176:179], v[228:231], v[58:61]
	ds_read_b128 v[192:195], v246 offset:34816
	v_mfma_f32_16x16x32_bf16 v[54:57], v[180:183], v[228:231], v[54:57]
	ds_read_b128 v[200:203], v246 offset:36864
	v_mfma_f32_16x16x32_bf16 v[50:53], v[184:187], v[228:231], v[50:53]
	ds_read_b128 v[208:211], v246 offset:38912
	s_waitcnt lgkmcnt(6)
	v_mfma_f32_16x16x32_bf16 v[46:49], v[152:155], v[232:235], v[46:49]
	ds_read_b128 v[212:215], v247
	v_mfma_f32_16x16x32_bf16 v[42:45], v[176:179], v[232:235], v[42:45]
	ds_read_b128 v[216:219], v247 offset:2048
	v_mfma_f32_16x16x32_bf16 v[34:37], v[180:183], v[232:235], v[34:37]
	s_mov_b32 m0, s46
	v_lshl_add_u64 v[204:205], v[140:141], 0, s[8:9]
	v_mfma_f32_16x16x32_bf16 v[30:33], v[184:187], v[232:235], v[30:33]
	global_load_lds_dwordx4 v[204:205], off
	s_mov_b32 m0, s47
	v_lshl_add_u64 v[204:205], v[140:141], 0, s[10:11]
	global_load_lds_dwordx4 v[204:205], off
	v_lshl_add_u64 v[138:139], v[138:139], 0, s[12:13]
	v_lshl_add_u64 v[140:141], v[140:141], 0, s[12:13]
	s_waitcnt lgkmcnt(7)
	v_mfma_f32_16x16x32_bf16 v[26:29], v[152:155], v[236:239], v[26:29]
	ds_read_b128 v[220:223], v247 offset:4096
	v_mfma_f32_16x16x32_bf16 v[22:25], v[176:179], v[236:239], v[22:25]
	ds_read_b128 v[224:227], v247 offset:6144
	v_mfma_f32_16x16x32_bf16 v[18:21], v[180:183], v[236:239], v[18:21]
	v_mfma_f32_16x16x32_bf16 v[14:17], v[184:187], v[236:239], v[14:17]
	s_waitcnt lgkmcnt(8)
	v_mfma_f32_16x16x32_bf16 v[10:13], v[152:155], v[240:243], v[10:13]
	v_mfma_f32_16x16x32_bf16 v[6:9], v[176:179], v[240:243], v[6:9]
	v_mfma_f32_16x16x32_bf16 v[2:5], v[180:183], v[240:243], v[2:5]
	v_mfma_f32_16x16x32_bf16 v[38:41], v[184:187], v[240:243], v[38:41]
	s_waitcnt lgkmcnt(3)
	v_mfma_f32_16x16x32_bf16 v[126:129], v[188:191], v[212:215], v[126:129]
	ds_read_b128 v[228:231], v247 offset:8192
	v_mfma_f32_16x16x32_bf16 v[122:125], v[192:195], v[212:215], v[122:125]
	ds_read_b128 v[232:235], v247 offset:10240
	v_mfma_f32_16x16x32_bf16 v[118:121], v[200:203], v[212:215], v[118:121]
	v_mfma_f32_16x16x32_bf16 v[114:117], v[208:211], v[212:215], v[114:117]
	s_waitcnt lgkmcnt(4)
	v_mfma_f32_16x16x32_bf16 v[110:113], v[188:191], v[216:219], v[110:113]
	v_mfma_f32_16x16x32_bf16 v[106:109], v[192:195], v[216:219], v[106:109]
	v_mfma_f32_16x16x32_bf16 v[102:105], v[200:203], v[216:219], v[102:105]
	v_mfma_f32_16x16x32_bf16 v[98:101], v[208:211], v[216:219], v[98:101]
	s_waitcnt lgkmcnt(3)
	v_mfma_f32_16x16x32_bf16 v[94:97], v[188:191], v[220:223], v[94:97]
	ds_read_b128 v[236:239], v247 offset:12288
	v_mfma_f32_16x16x32_bf16 v[90:93], v[192:195], v[220:223], v[90:93]
	ds_read_b128 v[240:243], v247 offset:14336
	v_mfma_f32_16x16x32_bf16 v[86:89], v[200:203], v[220:223], v[86:89]
	v_mfma_f32_16x16x32_bf16 v[82:85], v[208:211], v[220:223], v[82:85]
	s_waitcnt lgkmcnt(4)
	v_mfma_f32_16x16x32_bf16 v[78:81], v[188:191], v[224:227], v[78:81]
	v_mfma_f32_16x16x32_bf16 v[74:77], v[192:195], v[224:227], v[74:77]
	v_mfma_f32_16x16x32_bf16 v[70:73], v[200:203], v[224:227], v[70:73]
	v_mfma_f32_16x16x32_bf16 v[66:69], v[208:211], v[224:227], v[66:69]
	s_add_i32 s25, s25, 0x10000
; #define GLDS_STAGE(st, kt_) do { \
;         _Pragma("unroll") for (int i_ = 0; i_ < FI; ++i_) { \
;             glds16(ap + (size_t)(32 * i_) * lda + (kt_) * 64, l3a + (st) + tid * 16 + i_ * 4096); \
;             glds16(bp + (size_t)(32 * i_) * ldb + (kt_) * 64, l3a + (st) + OPB + tid * 16 + i_ * 4096); } } while (0)
; #define GLDS_STAGE(st, kt_) do { \
;         _Pragma("unroll") for (int i_ = 0; i_ < 4; ++i_) { \
;             glds16(ap + (size_t)(64 * i_) * lda + (kt_) * 64, l3a + (st) + tid * 16 + i_ * 8192); \
;             glds16(bp + (size_t)(64 * i_) * ldb + (kt_) * 64, l3a + (st) + 32768 + tid * 16 + i_ * 8192); } } while (0)
; template <class Epi>
; DEV void gemm256_tile(const bf16_t* __restrict__ A, int lda, const bf16_t* __restrict__ Bt, int ldb, int K, unsigned char* lds, const Epi& epi) {
;     ...
;     GLDS_STAGE(0, 0);
;     const int aoff = (wr * 128 + fr) * 128, boff = 32768 + (wc * 64 + fr) * 128, sw = fr & 7;
;     for (int kt = 0; kt < nk; ++kt) {
;         const int cur = (kt & 1) * 65536;
;         asm volatile("s_waitcnt vmcnt(0)" ::: "memory");
;         __syncthreads();
;         if (kt + 1 < nk) GLDS_STAGE(cur ^ 65536, kt + 1);
; #pragma unroll
;         for (int kh = 0; kh < 2; ++kh) {
;             bf16x8 bfr[4];
;             const int ch = ((kh * 4 + fq) ^ sw) << 4;
; #pragma unroll
;             for (int i = 0; i < 4; ++i) bfr[i] = *(const bf16x8*)(lds + cur + boff + i * 2048 + ch);
; #pragma unroll
;             for (int mh = 0; mh < 2; ++mh) {
;                 bf16x8 af[4];
; #pragma unroll
;                 for (int i = 0; i < 4; ++i) af[i] = *(const bf16x8*)(lds + cur + aoff + (mh * 4 + i) * 2048 + ch);
; #pragma unroll
;                 for (int mi = 0; mi < 4; ++mi)
; #pragma unroll
;                     for (int ni = 0; ni < 4; ++ni) acc[mh * 4 + mi][ni] = __builtin_amdgcn_mfma_f32_16x16x32_bf16(bfr[ni], af[mi], acc[mh * 4 + mi][ni], 0, 0, 0);
;             }
;         }
.Lg256r_b:
	s_and_b32 s48, s25, 0x10000
	s_xor_b32 s49, s48, 0x10000
	v_add_u32_e32 v206, s49, v136
	v_add_u32_e32 v207, s49, v150
	s_waitcnt vmcnt(0) lgkmcnt(0)
	s_barrier
	v_or_b32_e32 v248, s48, v151
	v_add_u32_e32 v249, s48, v148
	v_add_u32_e32 v244, v248, v149
	v_add_u32_e32 v245, v249, v149
	v_add_u32_e32 v246, v248, v147
	v_add_u32_e32 v247, v249, v147
	ds_read_b128 v[152:155], v244 offset:32768
	ds_read_b128 v[212:215], v245
	ds_read_b128 v[176:179], v244 offset:34816
	ds_read_b128 v[180:183], v244 offset:36864
	ds_read_b128 v[184:187], v244 offset:38912
	ds_read_b128 v[216:219], v245 offset:2048
	ds_read_b128 v[220:223], v245 offset:4096
	ds_read_b128 v[224:227], v245 offset:6144
	v_readfirstlane_b32 s40, v206
	v_readfirstlane_b32 s44, v207
	s_nop 0
	s_add_i32 s41, s40, 0x2000
	s_add_i32 s45, s44, 0x2000
	s_add_i32 s42, s40, 0x4000
	s_add_i32 s46, s44, 0x4000
	s_add_i32 s43, s40, 0x6000
	s_add_i32 s47, s44, 0x6000
	v_mfma_f32_16x16x32_bf16 v[62:65], v[188:191], v[228:231], v[62:65]
	s_mov_b32 m0, s40
	v_mfma_f32_16x16x32_bf16 v[58:61], v[192:195], v[228:231], v[58:61]
	global_load_lds_dwordx4 v[138:139], off
	v_mfma_f32_16x16x32_bf16 v[54:57], v[200:203], v[228:231], v[54:57]
	s_mov_b32 m0, s41
	v_lshl_add_u64 v[204:205], v[138:139], 0, s[6:7]
	v_mfma_f32_16x16x32_bf16 v[50:53], v[208:211], v[228:231], v[50:53]
	global_load_lds_dwordx4 v[204:205], off
	v_mfma_f32_16x16x32_bf16 v[46:49], v[188:191], v[232:235], v[46:49]
	s_mov_b32 m0, s42
	v_lshl_add_u64 v[204:205], v[138:139], 0, s[8:9]
	v_mfma_f32_16x16x32_bf16 v[42:45], v[192:195], v[232:235], v[42:45]
	global_load_lds_dwordx4 v[204:205], off
	v_mfma_f32_16x16x32_bf16 v[34:37], v[200:203], v[232:235], v[34:37]
	s_mov_b32 m0, s43
	v_lshl_add_u64 v[204:205], v[138:139], 0, s[10:11]
	v_mfma_f32_16x16x32_bf16 v[30:33], v[208:211], v[232:235], v[30:33]
	global_load_lds_dwordx4 v[204:205], off
	v_mfma_f32_16x16x32_bf16 v[26:29], v[188:191], v[236:239], v[26:29]
	s_mov_b32 m0, s44
	v_mfma_f32_16x16x32_bf16 v[22:25], v[192:195], v[236:239], v[22:25]
	global_load_lds_dwordx4 v[140:141], off
	v_mfma_f32_16x16x32_bf16 v[18:21], v[200:203], v[236:239], v[18:21]
	s_mov_b32 m0, s45
	v_lshl_add_u64 v[204:205], v[140:141], 0, s[6:7]
	v_mfma_f32_16x16x32_bf16 v[14:17], v[208:211], v[236:239], v[14:17]
	global_load_lds_dwordx4 v[204:205], off
	v_mfma_f32_16x16x32_bf16 v[10:13], v[188:191], v[240:243], v[10:13]
	s_mov_b32 m0, s46
	v_lshl_add_u64 v[204:205], v[140:141], 0, s[8:9]
	v_mfma_f32_16x16x32_bf16 v[6:9], v[192:195], v[240:243], v[6:9]
	global_load_lds_dwordx4 v[204:205], off
	v_mfma_f32_16x16x32_bf16 v[2:5], v[200:203], v[240:243], v[2:5]
	s_mov_b32 m0, s47
	v_lshl_add_u64 v[204:205], v[140:141], 0, s[10:11]
	v_mfma_f32_16x16x32_bf16 v[38:41], v[208:211], v[240:243], v[38:41]
	global_load_lds_dwordx4 v[204:205], off
	v_lshl_add_u64 v[138:139], v[138:139], 0, s[12:13]
	v_lshl_add_u64 v[140:141], v[140:141], 0, s[12:13]
	s_waitcnt lgkmcnt(6)
	v_mfma_f32_16x16x32_bf16 v[126:129], v[152:155], v[212:215], v[126:129]
	ds_read_b128 v[228:231], v245 offset:8192
	s_waitcnt lgkmcnt(6)
	v_mfma_f32_16x16x32_bf16 v[122:125], v[176:179], v[212:215], v[122:125]
	ds_read_b128 v[232:235], v245 offset:10240
	s_waitcnt lgkmcnt(6)
	v_mfma_f32_16x16x32_bf16 v[118:121], v[180:183], v[212:215], v[118:121]
	s_waitcnt lgkmcnt(5)
	v_mfma_f32_16x16x32_bf16 v[114:117], v[184:187], v[212:215], v[114:117]
	s_waitcnt lgkmcnt(4)
	v_mfma_f32_16x16x32_bf16 v[110:113], v[152:155], v[216:219], v[110:113]
	v_mfma_f32_16x16x32_bf16 v[106:109], v[176:179], v[216:219], v[106:109]
	v_mfma_f32_16x16x32_bf16 v[102:105], v[180:183], v[216:219], v[102:105]
	v_mfma_f32_16x16x32_bf16 v[98:101], v[184:187], v[216:219], v[98:101]
	s_waitcnt lgkmcnt(3)
	v_mfma_f32_16x16x32_bf16 v[94:97], v[152:155], v[220:223], v[94:97]
	ds_read_b128 v[236:239], v245 offset:12288
	v_mfma_f32_16x16x32_bf16 v[90:93], v[176:179], v[220:223], v[90:93]
	ds_read_b128 v[240:243], v245 offset:14336
	v_mfma_f32_16x16x32_bf16 v[86:89], v[180:183], v[220:223], v[86:89]
	v_mfma_f32_16x16x32_bf16 v[82:85], v[184:187], v[220:223], v[82:85]
	s_waitcnt lgkmcnt(4)
	v_mfma_f32_16x16x32_bf16 v[78:81], v[152:155], v[224:227], v[78:81]
	v_mfma_f32_16x16x32_bf16 v[74:77], v[176:179], v[224:227], v[74:77]
	v_mfma_f32_16x16x32_bf16 v[70:73], v[180:183], v[224:227], v[70:73]
	v_mfma_f32_16x16x32_bf16 v[66:69], v[184:187], v[224:227], v[66:69]
	s_waitcnt lgkmcnt(3)
	v_mfma_f32_16x16x32_bf16 v[62:65], v[152:155], v[228:231], v[62:65]
	ds_read_b128 v[188:191], v246 offset:32768
	v_mfma_f32_16x16x32_bf16 v[58:61], v[176:179], v[228:231], v[58:61]
	ds_read_b128 v[192:195], v246 offset:34816
	v_mfma_f32_16x16x32_bf16 v[54:57], v[180:183], v[228:231], v[54:57]
	ds_read_b128 v[200:203], v246 offset:36864
	v_mfma_f32_16x16x32_bf16 v[50:53], v[184:187], v[228:231], v[50:53]
	ds_read_b128 v[208:211], v246 offset:38912
	s_waitcnt lgkmcnt(6)
	v_mfma_f32_16x16x32_bf16 v[46:49], v[152:155], v[232:235], v[46:49]
	ds_read_b128 v[212:215], v247
	v_mfma_f32_16x16x32_bf16 v[42:45], v[176:179], v[232:235], v[42:45]
	ds_read_b128 v[216:219], v247 offset:2048
	v_mfma_f32_16x16x32_bf16 v[34:37], v[180:183], v[232:235], v[34:37]
	v_mfma_f32_16x16x32_bf16 v[30:33], v[184:187], v[232:235], v[30:33]
	s_waitcnt lgkmcnt(7)
	v_mfma_f32_16x16x32_bf16 v[26:29], v[152:155], v[236:239], v[26:29]
	ds_read_b128 v[220:223], v247 offset:4096
	v_mfma_f32_16x16x32_bf16 v[22:25], v[176:179], v[236:239], v[22:25]
	ds_read_b128 v[224:227], v247 offset:6144
	v_mfma_f32_16x16x32_bf16 v[18:21], v[180:183], v[236:239], v[18:21]
	v_mfma_f32_16x16x32_bf16 v[14:17], v[184:187], v[236:239], v[14:17]
	s_waitcnt lgkmcnt(8)
; #define GLDS_STAGE(st, kt_) do { \
;         _Pragma("unroll") for (int i_ = 0; i_ < FI; ++i_) { \
;             glds16(ap + (size_t)(32 * i_) * lda + (kt_) * 64, l3a + (st) + tid * 16 + i_ * 4096); \
;             glds16(bp + (size_t)(32 * i_) * ldb + (kt_) * 64, l3a + (st) + OPB + tid * 16 + i_ * 4096); } } while (0)
; #define GLDS_STAGE(st, kt_) do { \
;         _Pragma("unroll") for (int i_ = 0; i_ < 4; ++i_) { \
;             glds16(ap + (size_t)(64 * i_) * lda + (kt_) * 64, l3a + (st) + tid * 16 + i_ * 8192); \
;             glds16(bp + (size_t)(64 * i_) * ldb + (kt_) * 64, l3a + (st) + 32768 + tid * 16 + i_ * 8192); } } while (0)
; template <class Epi>
; DEV void gemm256_tile(const bf16_t* __restrict__ A, int lda, const bf16_t* __restrict__ Bt, int ldb, int K, unsigned char* lds, const Epi& epi) {
;     ...
;     for (int kt = 0; kt < nk; ++kt) {
;         const int cur = (kt & 1) * 65536;
;         asm volatile("s_waitcnt vmcnt(0)" ::: "memory");
;         __syncthreads();
;         if (kt + 1 < nk) GLDS_STAGE(cur ^ 65536, kt + 1);
; #pragma unroll
;         for (int kh = 0; kh < 2; ++kh) {
;             bf16x8 bfr[4];
;             const int ch = ((kh * 4 + fq) ^ sw) << 4;
; #pragma unroll
;             for (int i = 0; i < 4; ++i) bfr[i] = *(const bf16x8*)(lds + cur + boff + i * 2048 + ch);
; #pragma unroll
;             for (int mh = 0; mh < 2; ++mh) {
;                 bf16x8 af[4];
; #pragma unroll
;                 for (int i = 0; i < 4; ++i) af[i] = *(const bf16x8*)(lds + cur + aoff + (mh * 4 + i) * 2048 + ch);
; #pragma unroll
;                 for (int mi = 0; mi < 4; ++mi)
; #pragma unroll
;                     for (int ni = 0; ni < 4; ++ni) acc[mh * 4 + mi][ni] = __builtin_amdgcn_mfma_f32_16x16x32_bf16(bfr[ni], af[mi], acc[mh * 4 + mi][ni], 0, 0, 0);
;             }
;         }
	v_mfma_f32_16x16x32_bf16 v[10:13], v[152:155], v[240:243], v[10:13]
	v_mfma_f32_16x16x32_bf16 v[6:9], v[176:179], v[240:243], v[6:9]
	v_mfma_f32_16x16x32_bf16 v[2:5], v[180:183], v[240:243], v[2:5]
	v_mfma_f32_16x16x32_bf16 v[38:41], v[184:187], v[240:243], v[38:41]
	s_waitcnt lgkmcnt(3)
	v_mfma_f32_16x16x32_bf16 v[126:129], v[188:191], v[212:215], v[126:129]
	ds_read_b128 v[228:231], v247 offset:8192
	v_mfma_f32_16x16x32_bf16 v[122:125], v[192:195], v[212:215], v[122:125]
	ds_read_b128 v[232:235], v247 offset:10240
	v_mfma_f32_16x16x32_bf16 v[118:121], v[200:203], v[212:215], v[118:121]
	v_mfma_f32_16x16x32_bf16 v[114:117], v[208:211], v[212:215], v[114:117]
	s_waitcnt lgkmcnt(4)
	v_mfma_f32_16x16x32_bf16 v[110:113], v[188:191], v[216:219], v[110:113]
	v_mfma_f32_16x16x32_bf16 v[106:109], v[192:195], v[216:219], v[106:109]
	v_mfma_f32_16x16x32_bf16 v[102:105], v[200:203], v[216:219], v[102:105]
	v_mfma_f32_16x16x32_bf16 v[98:101], v[208:211], v[216:219], v[98:101]
	s_waitcnt lgkmcnt(3)
	v_mfma_f32_16x16x32_bf16 v[94:97], v[188:191], v[220:223], v[94:97]
	ds_read_b128 v[236:239], v247 offset:12288
	v_mfma_f32_16x16x32_bf16 v[90:93], v[192:195], v[220:223], v[90:93]
	ds_read_b128 v[240:243], v247 offset:14336
	v_mfma_f32_16x16x32_bf16 v[86:89], v[200:203], v[220:223], v[86:89]
	v_mfma_f32_16x16x32_bf16 v[82:85], v[208:211], v[220:223], v[82:85]
	s_waitcnt lgkmcnt(4)
	v_mfma_f32_16x16x32_bf16 v[78:81], v[188:191], v[224:227], v[78:81]
	v_mfma_f32_16x16x32_bf16 v[74:77], v[192:195], v[224:227], v[74:77]
	v_mfma_f32_16x16x32_bf16 v[70:73], v[200:203], v[224:227], v[70:73]
	v_mfma_f32_16x16x32_bf16 v[66:69], v[208:211], v[224:227], v[66:69]
	s_add_i32 s25, s25, 0x10000
	s_cmp_eq_u32 s25, 0x1f0000
	s_cbranch_scc0 .Lg256r_b
	s_waitcnt lgkmcnt(0)
	v_mfma_f32_16x16x32_bf16 v[62:65], v[188:191], v[228:231], v[62:65]
	v_mfma_f32_16x16x32_bf16 v[58:61], v[192:195], v[228:231], v[58:61]
	v_mfma_f32_16x16x32_bf16 v[54:57], v[200:203], v[228:231], v[54:57]
	v_mfma_f32_16x16x32_bf16 v[50:53], v[208:211], v[228:231], v[50:53]
	v_mfma_f32_16x16x32_bf16 v[46:49], v[188:191], v[232:235], v[46:49]
	v_mfma_f32_16x16x32_bf16 v[42:45], v[192:195], v[232:235], v[42:45]
	v_mfma_f32_16x16x32_bf16 v[34:37], v[200:203], v[232:235], v[34:37]
	v_mfma_f32_16x16x32_bf16 v[30:33], v[208:211], v[232:235], v[30:33]
	v_mfma_f32_16x16x32_bf16 v[26:29], v[188:191], v[236:239], v[26:29]
	v_mfma_f32_16x16x32_bf16 v[22:25], v[192:195], v[236:239], v[22:25]
	v_mfma_f32_16x16x32_bf16 v[18:21], v[200:203], v[236:239], v[18:21]
	v_mfma_f32_16x16x32_bf16 v[14:17], v[208:211], v[236:239], v[14:17]
	v_mfma_f32_16x16x32_bf16 v[10:13], v[188:191], v[240:243], v[10:13]
	v_mfma_f32_16x16x32_bf16 v[6:9], v[192:195], v[240:243], v[6:9]
	v_mfma_f32_16x16x32_bf16 v[2:5], v[200:203], v[240:243], v[2:5]
	v_mfma_f32_16x16x32_bf16 v[38:41], v[208:211], v[240:243], v[38:41]
	v_or_b32_e32 v172, 0x18000, v151
	v_add_u32_e32 v156, v172, v149
	s_waitcnt vmcnt(0)
	s_barrier
	ds_read_b128 v[138:141], v156
	ds_read_b128 v[152:155], v156 offset:2048
	ds_read_b128 v[176:179], v156 offset:4096
	ds_read_b128 v[180:183], v156 offset:6144
	v_add_u32_e32 v173, 0x10000, v148
	v_add_u32_e32 v188, v173, v149
	ds_read_b128 v[148:151], v188
	s_waitcnt lgkmcnt(0)
	v_mfma_f32_16x16x32_bf16 v[126:129], v[138:141], v[148:151], v[126:129]
	s_sext_i32_i8 s14, s24
	s_lshl_b32 s24, s14, 8
	s_lshl_b64 s[16:17], s[16:17], 21
	v_mfma_f32_16x16x32_bf16 v[122:125], v[152:155], v[148:151], v[122:125]
	s_ashr_i32 s25, s24, 31
	s_add_u32 s14, s4, s16
	s_addc_u32 s15, s5, s17
	v_mfma_f32_16x16x32_bf16 v[118:121], v[176:179], v[148:151], v[118:121]
	s_lshl_b64 s[16:17], s[24:25], 2
	v_lshl_add_u64 v[156:157], v[130:131], 0, s[18:19]
	s_add_u32 s16, s14, s16
	v_mfma_f32_16x16x32_bf16 v[114:117], v[180:183], v[148:151], v[114:117]
	ds_read_b128 v[148:151], v188 offset:2048
	s_addc_u32 s17, s15, s17
	s_mov_b32 s18, 0
	s_waitcnt lgkmcnt(0)
	v_mfma_f32_16x16x32_bf16 v[110:113], v[138:141], v[148:151], v[110:113]
	v_mfma_f32_16x16x32_bf16 v[106:109], v[152:155], v[148:151], v[106:109]
	v_mfma_f32_16x16x32_bf16 v[102:105], v[176:179], v[148:151], v[102:105]
	v_mfma_f32_16x16x32_bf16 v[98:101], v[180:183], v[148:151], v[98:101]
	ds_read_b128 v[148:151], v188 offset:4096
	s_waitcnt lgkmcnt(0)
	v_mfma_f32_16x16x32_bf16 v[94:97], v[138:141], v[148:151], v[94:97]
	v_mfma_f32_16x16x32_bf16 v[90:93], v[152:155], v[148:151], v[90:93]
	v_mfma_f32_16x16x32_bf16 v[86:89], v[176:179], v[148:151], v[86:89]
	v_mfma_f32_16x16x32_bf16 v[82:85], v[180:183], v[148:151], v[82:85]
	ds_read_b128 v[148:151], v188 offset:6144
	s_waitcnt lgkmcnt(0)
	v_mfma_f32_16x16x32_bf16 v[78:81], v[138:141], v[148:151], v[78:81]
	v_mfma_f32_16x16x32_bf16 v[74:77], v[152:155], v[148:151], v[74:77]
	v_mfma_f32_16x16x32_bf16 v[70:73], v[176:179], v[148:151], v[70:73]
	v_mfma_f32_16x16x32_bf16 v[66:69], v[180:183], v[148:151], v[66:69]
	ds_read_b128 v[148:151], v188 offset:8192
	ds_read_b128 v[184:187], v188 offset:10240
	s_waitcnt lgkmcnt(1)
	v_mfma_f32_16x16x32_bf16 v[62:65], v[138:141], v[148:151], v[62:65]
	v_mfma_f32_16x16x32_bf16 v[58:61], v[152:155], v[148:151], v[58:61]
	v_mfma_f32_16x16x32_bf16 v[54:57], v[176:179], v[148:151], v[54:57]
	v_mfma_f32_16x16x32_bf16 v[50:53], v[180:183], v[148:151], v[50:53]
	ds_read_b128 v[148:151], v188 offset:12288
	s_waitcnt lgkmcnt(1)
	v_mfma_f32_16x16x32_bf16 v[46:49], v[138:141], v[184:187], v[46:49]
	v_mfma_f32_16x16x32_bf16 v[42:45], v[152:155], v[184:187], v[42:45]
	v_mfma_f32_16x16x32_bf16 v[34:37], v[176:179], v[184:187], v[34:37]
	v_mfma_f32_16x16x32_bf16 v[30:33], v[180:183], v[184:187], v[30:33]
	ds_read_b128 v[184:187], v188 offset:14336
	s_waitcnt lgkmcnt(1)
; DEV unsigned cvt_pk_bf16(float lo, float hi) { const f32x2_t v = {lo, hi}; const bf16x2_t b = __builtin_convertvector(v, bf16x2_t); return __builtin_bit_cast(unsigned, b); }
; template <class Epi>
; DEV void gemm256_tile(const bf16_t* __restrict__ A, int lda, const bf16_t* __restrict__ Bt, int ldb, int K, unsigned char* lds, const Epi& epi) {
;     ...
; #pragma unroll
;         for (int kh = 0; kh < 2; ++kh) {
;             bf16x8 bfr[4];
;             const int ch = ((kh * 4 + fq) ^ sw) << 4;
; #pragma unroll
;             for (int i = 0; i < 4; ++i) bfr[i] = *(const bf16x8*)(lds + cur + boff + i * 2048 + ch);
; #pragma unroll
;             for (int mh = 0; mh < 2; ++mh) {
;                 bf16x8 af[4];
; #pragma unroll
;                 for (int i = 0; i < 4; ++i) af[i] = *(const bf16x8*)(lds + cur + aoff + (mh * 4 + i) * 2048 + ch);
; #pragma unroll
;                 for (int mi = 0; mi < 4; ++mi)
; #pragma unroll
;                     for (int ni = 0; ni < 4; ++ni) acc[mh * 4 + mi][ni] = __builtin_amdgcn_mfma_f32_16x16x32_bf16(bfr[ni], af[mi], acc[mh * 4 + mi][ni], 0, 0, 0);
;             }
;     ...
; #pragma unroll
;         for (int mi = 0; mi < 8; ++mi)
; #pragma unroll
;             for (int ni = 0; ni < 4; ++ni) {
;                 const int row = wr * 128 + mi * 16 + fr, col = wc * 64 + ni * 16 + fq * 4;
;                 const f32x4 v = epi.xform(row, col, acc[mi][ni]);
;                 uint2 w; w.x = cvt_pk_bf16(v[0], v[1]); w.y = cvt_pk_bf16(v[2], v[3]);
;                 *(uint2*)(lds + row * 512 + ((((col >> 3) ^ (row & 31)) << 4) | (((col >> 2) & 1) << 3))) = w;
	v_mfma_f32_16x16x32_bf16 v[188:191], v[138:141], v[148:151], v[26:29]
	s_nop 2
	v_add_u32_e32 v29, v172, v147
	ds_read_b128 v[192:195], v29
	ds_read_b128 v[196:199], v29 offset:2048
	ds_read_b128 v[200:203], v29 offset:4096
	ds_read_b128 v[204:207], v29 offset:6144
	v_add_u32_e32 v29, v173, v147
	v_mfma_f32_16x16x32_bf16 v[22:25], v[152:155], v[148:151], v[22:25]
	v_and_b32_e32 v28, 0xc0, v142
	v_lshl_or_b32 v145, v145, 2, v28
	v_lshlrev_b32_e32 v28, 3, v144
	v_mfma_f32_16x16x32_bf16 v[18:21], v[176:179], v[148:151], v[18:21]
	v_lshl_add_u64 v[26:27], s[24:25], 1, v[156:157]
	v_mfma_f32_16x16x32_bf16 v[14:17], v[180:183], v[148:151], v[14:17]
	ds_read_b128 v[148:151], v29
	ds_read_b128 v[208:211], v29 offset:2048
	ds_read_b128 v[212:215], v29 offset:4096
	ds_read_b128 v[216:219], v29 offset:6144
	s_waitcnt lgkmcnt(3)
	v_mfma_f32_16x16x32_bf16 v[126:129], v[192:195], v[148:151], v[126:129]
	v_mfma_f32_16x16x32_bf16 v[122:125], v[196:199], v[148:151], v[122:125]
	s_waitcnt lgkmcnt(1)
	v_mfma_f32_16x16x32_bf16 v[94:97], v[192:195], v[212:215], v[94:97]
	v_mfma_f32_16x16x32_bf16 v[10:13], v[138:141], v[184:187], v[10:13]
	ds_read_b128 v[138:141], v29 offset:8192
	ds_read_b128 v[220:223], v29 offset:10240
	ds_read_b128 v[224:227], v29 offset:12288
	ds_read_b128 v[228:231], v29 offset:14336
	v_lshlrev_b32_e32 v29, 9, v146
	v_and_or_b32 v144, v28, 8, v29
	v_mfma_f32_16x16x32_bf16 v[118:121], v[200:203], v[148:151], v[118:121]
	v_cvt_pk_bf16_f32 v28, v126, v127
	v_lshrrev_b32_e32 v126, 3, v145
	v_xor_b32_e32 v127, v126, v143
	v_mfma_f32_16x16x32_bf16 v[90:93], v[196:199], v[212:215], v[90:93]
	v_cvt_pk_bf16_f32 v29, v128, v129
	v_lshl_or_b32 v127, v127, 4, v144
	v_cvt_pk_bf16_f32 v122, v122, v123
	v_mfma_f32_16x16x32_bf16 v[114:117], v[204:207], v[148:151], v[114:117]
	v_cvt_pk_bf16_f32 v123, v124, v125
	v_bitop3_b32 v124, v126, v143, 2 bitop3:0x36
	v_cvt_pk_bf16_f32 v94, v94, v95
	v_mfma_f32_16x16x32_bf16 v[86:89], v[200:203], v[212:215], v[86:89]
	v_cvt_pk_bf16_f32 v95, v96, v97
	s_waitcnt lgkmcnt(0)
	s_barrier
; DEV unsigned cvt_pk_bf16(float lo, float hi) { const f32x2_t v = {lo, hi}; const bf16x2_t b = __builtin_convertvector(v, bf16x2_t); return __builtin_bit_cast(unsigned, b); }
; template <class Epi>
; DEV void gemm256_tile(const bf16_t* __restrict__ A, int lda, const bf16_t* __restrict__ Bt, int ldb, int K, unsigned char* lds, const Epi& epi) {
;     ...
; #pragma unroll
;         for (int mi = 0; mi < 8; ++mi)
; #pragma unroll
;             for (int ni = 0; ni < 4; ++ni) {
;                 const int row = wr * 128 + mi * 16 + fr, col = wc * 64 + ni * 16 + fq * 4;
;                 const f32x4 v = epi.xform(row, col, acc[mi][ni]);
;                 uint2 w; w.x = cvt_pk_bf16(v[0], v[1]); w.y = cvt_pk_bf16(v[2], v[3]);
;                 *(uint2*)(lds + row * 512 + ((((col >> 3) ^ (row & 31)) << 4) | (((col >> 2) & 1) << 3))) = w;
;             }
;         __syncthreads();
	v_mfma_f32_16x16x32_bf16 v[110:113], v[192:195], v[208:211], v[110:113]
	v_lshl_add_u32 v124, v124, 4, v144
	v_cvt_pk_bf16_f32 v118, v118, v119
	v_mfma_f32_16x16x32_bf16 v[82:85], v[204:207], v[212:215], v[82:85]
	v_cvt_pk_bf16_f32 v119, v120, v121
	v_bitop3_b32 v120, v126, v143, 4 bitop3:0x36
	ds_write2st64_b64 v127, v[28:29], v[94:95] offset1:32
	v_mfma_f32_16x16x32_bf16 v[106:109], v[196:199], v[208:211], v[106:109]
	v_cvt_pk_bf16_f32 v28, v90, v91
	v_cvt_pk_bf16_f32 v29, v92, v93
	v_lshl_add_u32 v120, v120, 4, v144
	v_mfma_f32_16x16x32_bf16 v[78:81], v[192:195], v[216:219], v[78:81]
	v_cvt_pk_bf16_f32 v114, v114, v115
	v_cvt_pk_bf16_f32 v115, v116, v117
	v_bitop3_b32 v116, v126, v143, 6 bitop3:0x36
	v_mfma_f32_16x16x32_bf16 v[102:105], v[200:203], v[208:211], v[102:105]
	ds_write2st64_b64 v124, v[122:123], v[28:29] offset1:32
	v_cvt_pk_bf16_f32 v28, v86, v87
	v_cvt_pk_bf16_f32 v29, v88, v89
	v_mfma_f32_16x16x32_bf16 v[74:77], v[196:199], v[216:219], v[74:77]
	v_lshl_add_u32 v116, v116, 4, v144
	v_or_b32_e32 v117, 16, v143
	v_cvt_pk_bf16_f32 v110, v110, v111
	v_mfma_f32_16x16x32_bf16 v[2:5], v[176:179], v[184:187], v[2:5]
	v_cvt_pk_bf16_f32 v111, v112, v113
	v_bitop3_b32 v112, v126, v143, 16 bitop3:0x1e
	ds_write2st64_b64 v120, v[118:119], v[28:29] offset1:32
	v_mfma_f32_16x16x32_bf16 v[98:101], v[204:207], v[208:211], v[98:101]
	v_cvt_pk_bf16_f32 v28, v82, v83
	v_cvt_pk_bf16_f32 v29, v84, v85
	v_lshl_or_b32 v112, v112, 4, v144
	v_mfma_f32_16x16x32_bf16 v[70:73], v[200:203], v[216:219], v[70:73]
	v_cvt_pk_bf16_f32 v106, v106, v107
	v_cvt_pk_bf16_f32 v107, v108, v109
	v_bitop3_b32 v108, v126, v117, 2 bitop3:0x36
	v_mfma_f32_16x16x32_bf16 v[66:69], v[204:207], v[216:219], v[66:69]
	ds_write2st64_b64 v116, v[114:115], v[28:29] offset1:32
	v_cvt_pk_bf16_f32 v28, v78, v79
	v_cvt_pk_bf16_f32 v29, v80, v81
	v_lshl_add_u32 v108, v108, 4, v144
	v_cvt_pk_bf16_f32 v102, v102, v103
	v_cvt_pk_bf16_f32 v103, v104, v105
	v_bitop3_b32 v104, v126, v117, 4 bitop3:0x36
	ds_write2st64_b64 v112, v[110:111], v[28:29] offset0:16 offset1:48
	v_cvt_pk_bf16_f32 v28, v74, v75
	v_cvt_pk_bf16_f32 v29, v76, v77
	v_lshl_add_u32 v104, v104, 4, v144
	v_cvt_pk_bf16_f32 v98, v98, v99
	v_cvt_pk_bf16_f32 v99, v100, v101
	v_bitop3_b32 v100, v126, v117, 6 bitop3:0x36
	ds_write2st64_b64 v108, v[106:107], v[28:29] offset0:16 offset1:48
	v_cvt_pk_bf16_f32 v28, v70, v71
	v_cvt_pk_bf16_f32 v29, v72, v73
	v_mfma_f32_16x16x32_bf16 v[34:37], v[200:203], v[220:223], v[34:37]
	v_lshl_add_u32 v100, v100, 4, v144
	ds_write2st64_b64 v104, v[102:103], v[28:29] offset0:16 offset1:48
	v_cvt_pk_bf16_f32 v28, v66, v67
	v_mfma_f32_16x16x32_bf16 v[2:5], v[200:203], v[228:231], v[2:5]
	v_cvt_pk_bf16_f32 v29, v68, v69
	ds_write2st64_b64 v100, v[98:99], v[28:29] offset0:16 offset1:48
	s_nop 1
	v_cvt_pk_bf16_f32 v34, v34, v35
	v_mfma_f32_16x16x32_bf16 v[38:41], v[180:183], v[184:187], v[38:41]
	v_cvt_pk_bf16_f32 v35, v36, v37
	s_nop 0
	v_cvt_pk_bf16_f32 v2, v2, v3
	v_cvt_pk_bf16_f32 v3, v4, v5
	v_mfma_f32_16x16x32_bf16 v[6:9], v[152:155], v[184:187], v[6:9]
	ds_write2st64_b64 v104, v[34:35], v[2:3] offset0:80 offset1:112
	v_mfma_f32_16x16x32_bf16 v[28:31], v[204:207], v[220:223], v[30:33]
	v_mfma_f32_16x16x32_bf16 v[2:5], v[204:207], v[228:231], v[38:41]
	v_mfma_f32_16x16x32_bf16 v[62:65], v[192:195], v[138:141], v[62:65]
	s_nop 5
	v_cvt_pk_bf16_f32 v32, v28, v29
	v_cvt_pk_bf16_f32 v33, v30, v31
	v_cvt_pk_bf16_f32 v2, v2, v3
	v_mfma_f32_16x16x32_bf16 v[58:61], v[196:199], v[138:141], v[58:61]
	v_cvt_pk_bf16_f32 v3, v4, v5
	v_cvt_pk_bf16_f32 v62, v62, v63
	v_cvt_pk_bf16_f32 v63, v64, v65
	v_mfma_f32_16x16x32_bf16 v[54:57], v[200:203], v[138:141], v[54:57]
	ds_write2st64_b64 v100, v[32:33], v[2:3] offset0:80 offset1:112
	s_nop 2
	v_cvt_pk_bf16_f32 v58, v58, v59
	v_cvt_pk_bf16_f32 v59, v60, v61
	v_mfma_f32_16x16x32_bf16 v[50:53], v[204:207], v[138:141], v[50:53]
	v_and_b32_e32 v2, 0x1f0, v136
	v_cvt_pk_bf16_f32 v54, v54, v55
	v_cvt_pk_bf16_f32 v55, v56, v57
	v_mfma_f32_16x16x32_bf16 v[46:49], v[192:195], v[220:223], v[46:49]
	v_mfma_f32_16x16x32_bf16 v[42:45], v[196:199], v[220:223], v[42:45]
	s_nop 2
	v_cvt_pk_bf16_f32 v50, v50, v51
	v_cvt_pk_bf16_f32 v51, v52, v53
	s_nop 1
	v_cvt_pk_bf16_f32 v46, v46, v47
	v_mfma_f32_16x16x32_bf16 v[28:31], v[192:195], v[224:227], v[188:191]
	v_cvt_pk_bf16_f32 v47, v48, v49
	v_cvt_pk_bf16_f32 v42, v42, v43
	v_cvt_pk_bf16_f32 v43, v44, v45
	v_mfma_f32_16x16x32_bf16 v[22:25], v[196:199], v[224:227], v[22:25]
	v_mfma_f32_16x16x32_bf16 v[18:21], v[200:203], v[224:227], v[18:21]
	s_nop 2
	v_cvt_pk_bf16_f32 v28, v28, v29
	v_cvt_pk_bf16_f32 v29, v30, v31
	s_nop 1
	v_cvt_pk_bf16_f32 v22, v22, v23
	v_mfma_f32_16x16x32_bf16 v[14:17], v[204:207], v[224:227], v[14:17]
	v_cvt_pk_bf16_f32 v23, v24, v25
	v_cvt_pk_bf16_f32 v18, v18, v19
	v_cvt_pk_bf16_f32 v19, v20, v21
	v_mfma_f32_16x16x32_bf16 v[10:13], v[192:195], v[228:231], v[10:13]
	ds_write2st64_b64 v127, v[62:63], v[28:29] offset0:64 offset1:96
	s_nop 2
	v_cvt_pk_bf16_f32 v14, v14, v15
	v_cvt_pk_bf16_f32 v15, v16, v17
	v_mfma_f32_16x16x32_bf16 v[6:9], v[196:199], v[228:231], v[6:9]
	ds_write2st64_b64 v124, v[58:59], v[22:23] offset0:64 offset1:96
	v_cvt_pk_bf16_f32 v10, v10, v11
	v_cvt_pk_bf16_f32 v11, v12, v13
	ds_write2st64_b64 v120, v[54:55], v[18:19] offset0:64 offset1:96
	ds_write2st64_b64 v116, v[50:51], v[14:15] offset0:64 offset1:96
	s_nop 2
	v_cvt_pk_bf16_f32 v6, v6, v7
	v_cvt_pk_bf16_f32 v7, v8, v9
	ds_write2st64_b64 v112, v[46:47], v[10:11] offset0:80 offset1:112
	ds_write2st64_b64 v108, v[42:43], v[6:7] offset0:80 offset1:112
	s_waitcnt lgkmcnt(0)
	s_barrier

; #define GLDS_STAGE(st, kt_) do { \
;         _Pragma("unroll") for (int i_ = 0; i_ < FI; ++i_) { \
;             glds16(ap + (size_t)(32 * i_) * lda + (kt_) * 64, l3a + (st) + tid * 16 + i_ * 4096); \
;             glds16(bp + (size_t)(32 * i_) * ldb + (kt_) * 64, l3a + (st) + OPB + tid * 16 + i_ * 4096); } } while (0)
; #define GLDS_STAGE(st, kt_) do { \
;         _Pragma("unroll") for (int i_ = 0; i_ < 4; ++i_) { \
;             glds16(ap + (size_t)(64 * i_) * lda + (kt_) * 64, l3a + (st) + tid * 16 + i_ * 8192); \
;             glds16(bp + (size_t)(64 * i_) * ldb + (kt_) * 64, l3a + (st) + 32768 + tid * 16 + i_ * 8192); } } while (0)
; template <class Epi>
; DEV void gemm256_tile(const bf16_t* __restrict__ A, int lda, const bf16_t* __restrict__ Bt, int ldb, int K, unsigned char* lds, const Epi& epi) {
;     ...
;     GLDS_STAGE(0, 0);
;     const int aoff = (wr * 128 + fr) * 128, boff = 32768 + (wc * 64 + fr) * 128, sw = fr & 7;
;     for (int kt = 0; kt < nk; ++kt) {
;         const int cur = (kt & 1) * 65536;
;         asm volatile("s_waitcnt vmcnt(0)" ::: "memory");
;         __syncthreads();
;         if (kt + 1 < nk) GLDS_STAGE(cur ^ 65536, kt + 1);
; #pragma unroll
;         for (int kh = 0; kh < 2; ++kh) {
;             bf16x8 bfr[4];
;             const int ch = ((kh * 4 + fq) ^ sw) << 4;
; #pragma unroll
;             for (int i = 0; i < 4; ++i) bfr[i] = *(const bf16x8*)(lds + cur + boff + i * 2048 + ch);
; #pragma unroll
;             for (int mh = 0; mh < 2; ++mh) {
;                 bf16x8 af[4];
; #pragma unroll
;                 for (int i = 0; i < 4; ++i) af[i] = *(const bf16x8*)(lds + cur + aoff + (mh * 4 + i) * 2048 + ch);
; #pragma unroll
;                 for (int mi = 0; mi < 4; ++mi)
; #pragma unroll
;                     for (int ni = 0; ni < 4; ++ni) acc[mh * 4 + mi][ni] = __builtin_amdgcn_mfma_f32_16x16x32_bf16(bfr[ni], af[mi], acc[mh * 4 + mi][ni], 0, 0, 0);
;             }
;         }
.LBB0_1236:
	s_and_b32 s48, s21, 0x10000
	s_xor_b32 s49, s48, 0x10000
	v_add_u32_e32 v206, s49, v138
	v_add_u32_e32 v207, s49, v150
	s_waitcnt vmcnt(0) lgkmcnt(0)
	s_barrier
	v_or_b32_e32 v248, s48, v153
	v_add_u32_e32 v249, s48, v151
	v_add_u32_e32 v244, v248, v152
	v_add_u32_e32 v245, v249, v152
	v_add_u32_e32 v246, v248, v149
	v_add_u32_e32 v247, v249, v149
	ds_read_b128 v[154:157], v244 offset:32768
	ds_read_b128 v[212:215], v245
	ds_read_b128 v[170:173], v244 offset:34816
	ds_read_b128 v[174:177], v244 offset:36864
	ds_read_b128 v[178:181], v244 offset:38912
	ds_read_b128 v[216:219], v245 offset:2048
	ds_read_b128 v[220:223], v245 offset:4096
	ds_read_b128 v[224:227], v245 offset:6144
	v_readfirstlane_b32 s40, v206
	v_readfirstlane_b32 s44, v207
	s_nop 0
	s_add_i32 s41, s40, 0x2000
	s_add_i32 s45, s44, 0x2000
	s_add_i32 s42, s40, 0x4000
	s_add_i32 s46, s44, 0x4000
	s_add_i32 s43, s40, 0x6000
	s_add_i32 s47, s44, 0x6000
	s_waitcnt lgkmcnt(6)
	v_mfma_f32_16x16x32_bf16 v[126:129], v[154:157], v[212:215], v[126:129]
	ds_read_b128 v[228:231], v245 offset:8192
	s_waitcnt lgkmcnt(6)
	v_mfma_f32_16x16x32_bf16 v[122:125], v[170:173], v[212:215], v[122:125]
	ds_read_b128 v[232:235], v245 offset:10240
	s_waitcnt lgkmcnt(6)
	v_mfma_f32_16x16x32_bf16 v[118:121], v[174:177], v[212:215], v[118:121]
	s_mov_b32 m0, s40
	s_waitcnt lgkmcnt(5)
	v_mfma_f32_16x16x32_bf16 v[114:117], v[178:181], v[212:215], v[114:117]
	global_load_lds_dwordx4 v[140:141], off
	s_waitcnt lgkmcnt(4)
	v_mfma_f32_16x16x32_bf16 v[110:113], v[154:157], v[216:219], v[110:113]
	s_mov_b32 m0, s41
	v_lshl_add_u64 v[204:205], v[140:141], 0, s[4:5]
	v_mfma_f32_16x16x32_bf16 v[106:109], v[170:173], v[216:219], v[106:109]
	global_load_lds_dwordx4 v[204:205], off
	v_mfma_f32_16x16x32_bf16 v[102:105], v[174:177], v[216:219], v[102:105]
	s_mov_b32 m0, s42
	v_lshl_add_u64 v[204:205], v[140:141], 0, s[6:7]
	v_mfma_f32_16x16x32_bf16 v[98:101], v[178:181], v[216:219], v[98:101]
	global_load_lds_dwordx4 v[204:205], off
	s_waitcnt lgkmcnt(3)
	v_mfma_f32_16x16x32_bf16 v[94:97], v[154:157], v[220:223], v[94:97]
	ds_read_b128 v[236:239], v245 offset:12288
	v_mfma_f32_16x16x32_bf16 v[90:93], v[170:173], v[220:223], v[90:93]
	ds_read_b128 v[240:243], v245 offset:14336
	v_mfma_f32_16x16x32_bf16 v[86:89], v[174:177], v[220:223], v[86:89]
	s_mov_b32 m0, s43
	v_lshl_add_u64 v[204:205], v[140:141], 0, s[8:9]
	v_mfma_f32_16x16x32_bf16 v[82:85], v[178:181], v[220:223], v[82:85]
	global_load_lds_dwordx4 v[204:205], off
	s_waitcnt lgkmcnt(4)
	v_mfma_f32_16x16x32_bf16 v[78:81], v[154:157], v[224:227], v[78:81]
	s_mov_b32 m0, s44
	v_mfma_f32_16x16x32_bf16 v[74:77], v[170:173], v[224:227], v[74:77]
	global_load_lds_dwordx4 v[142:143], off
	v_mfma_f32_16x16x32_bf16 v[70:73], v[174:177], v[224:227], v[70:73]
	s_mov_b32 m0, s45
	v_lshl_add_u64 v[204:205], v[142:143], 0, s[4:5]
	v_mfma_f32_16x16x32_bf16 v[66:69], v[178:181], v[224:227], v[66:69]
	global_load_lds_dwordx4 v[204:205], off
	s_waitcnt lgkmcnt(3)
	v_mfma_f32_16x16x32_bf16 v[62:65], v[154:157], v[228:231], v[62:65]
	ds_read_b128 v[182:185], v246 offset:32768
	v_mfma_f32_16x16x32_bf16 v[58:61], v[170:173], v[228:231], v[58:61]
	ds_read_b128 v[186:189], v246 offset:34816
	v_mfma_f32_16x16x32_bf16 v[54:57], v[174:177], v[228:231], v[54:57]
	ds_read_b128 v[200:203], v246 offset:36864
	v_mfma_f32_16x16x32_bf16 v[50:53], v[178:181], v[228:231], v[50:53]
	ds_read_b128 v[208:211], v246 offset:38912
	s_waitcnt lgkmcnt(6)
	v_mfma_f32_16x16x32_bf16 v[46:49], v[154:157], v[232:235], v[46:49]
	ds_read_b128 v[212:215], v247
	v_mfma_f32_16x16x32_bf16 v[42:45], v[170:173], v[232:235], v[42:45]
	ds_read_b128 v[216:219], v247 offset:2048
	v_mfma_f32_16x16x32_bf16 v[34:37], v[174:177], v[232:235], v[34:37]
	s_mov_b32 m0, s46
	v_lshl_add_u64 v[204:205], v[142:143], 0, s[6:7]
	v_mfma_f32_16x16x32_bf16 v[30:33], v[178:181], v[232:235], v[30:33]
	global_load_lds_dwordx4 v[204:205], off
	s_mov_b32 m0, s47
	v_lshl_add_u64 v[204:205], v[142:143], 0, s[8:9]
	global_load_lds_dwordx4 v[204:205], off
	v_lshl_add_u64 v[140:141], v[140:141], 0, s[10:11]
	v_lshl_add_u64 v[142:143], v[142:143], 0, s[10:11]
	s_waitcnt lgkmcnt(7)
	v_mfma_f32_16x16x32_bf16 v[26:29], v[154:157], v[236:239], v[26:29]
	ds_read_b128 v[220:223], v247 offset:4096
	v_mfma_f32_16x16x32_bf16 v[22:25], v[170:173], v[236:239], v[22:25]
	ds_read_b128 v[224:227], v247 offset:6144
	v_mfma_f32_16x16x32_bf16 v[18:21], v[174:177], v[236:239], v[18:21]
	v_mfma_f32_16x16x32_bf16 v[14:17], v[178:181], v[236:239], v[14:17]
	s_waitcnt lgkmcnt(8)
	v_mfma_f32_16x16x32_bf16 v[10:13], v[154:157], v[240:243], v[10:13]
	v_mfma_f32_16x16x32_bf16 v[6:9], v[170:173], v[240:243], v[6:9]
	v_mfma_f32_16x16x32_bf16 v[2:5], v[174:177], v[240:243], v[2:5]
	v_mfma_f32_16x16x32_bf16 v[38:41], v[178:181], v[240:243], v[38:41]
	s_waitcnt lgkmcnt(3)
	v_mfma_f32_16x16x32_bf16 v[126:129], v[182:185], v[212:215], v[126:129]
	ds_read_b128 v[228:231], v247 offset:8192
	v_mfma_f32_16x16x32_bf16 v[122:125], v[186:189], v[212:215], v[122:125]
	ds_read_b128 v[232:235], v247 offset:10240
	v_mfma_f32_16x16x32_bf16 v[118:121], v[200:203], v[212:215], v[118:121]
	v_mfma_f32_16x16x32_bf16 v[114:117], v[208:211], v[212:215], v[114:117]
	s_waitcnt lgkmcnt(4)
	v_mfma_f32_16x16x32_bf16 v[110:113], v[182:185], v[216:219], v[110:113]
	v_mfma_f32_16x16x32_bf16 v[106:109], v[186:189], v[216:219], v[106:109]
	v_mfma_f32_16x16x32_bf16 v[102:105], v[200:203], v[216:219], v[102:105]
	v_mfma_f32_16x16x32_bf16 v[98:101], v[208:211], v[216:219], v[98:101]
	s_waitcnt lgkmcnt(3)
	v_mfma_f32_16x16x32_bf16 v[94:97], v[182:185], v[220:223], v[94:97]
	ds_read_b128 v[236:239], v247 offset:12288
	v_mfma_f32_16x16x32_bf16 v[90:93], v[186:189], v[220:223], v[90:93]
	ds_read_b128 v[240:243], v247 offset:14336
	v_mfma_f32_16x16x32_bf16 v[86:89], v[200:203], v[220:223], v[86:89]
	v_mfma_f32_16x16x32_bf16 v[82:85], v[208:211], v[220:223], v[82:85]
	s_waitcnt lgkmcnt(4)
	v_mfma_f32_16x16x32_bf16 v[78:81], v[182:185], v[224:227], v[78:81]
	v_mfma_f32_16x16x32_bf16 v[74:77], v[186:189], v[224:227], v[74:77]
	v_mfma_f32_16x16x32_bf16 v[70:73], v[200:203], v[224:227], v[70:73]
	v_mfma_f32_16x16x32_bf16 v[66:69], v[208:211], v[224:227], v[66:69]
	s_add_i32 s21, s21, 0x10000
; #define GLDS_STAGE(st, kt_) do { \
;         _Pragma("unroll") for (int i_ = 0; i_ < FI; ++i_) { \
;             glds16(ap + (size_t)(32 * i_) * lda + (kt_) * 64, l3a + (st) + tid * 16 + i_ * 4096); \
;             glds16(bp + (size_t)(32 * i_) * ldb + (kt_) * 64, l3a + (st) + OPB + tid * 16 + i_ * 4096); } } while (0)
; #define GLDS_STAGE(st, kt_) do { \
;         _Pragma("unroll") for (int i_ = 0; i_ < 4; ++i_) { \
;             glds16(ap + (size_t)(64 * i_) * lda + (kt_) * 64, l3a + (st) + tid * 16 + i_ * 8192); \
;             glds16(bp + (size_t)(64 * i_) * ldb + (kt_) * 64, l3a + (st) + 32768 + tid * 16 + i_ * 8192); } } while (0)
; template <class Epi>
; DEV void gemm256_tile(const bf16_t* __restrict__ A, int lda, const bf16_t* __restrict__ Bt, int ldb, int K, unsigned char* lds, const Epi& epi) {
;     ...
;     GLDS_STAGE(0, 0);
;     const int aoff = (wr * 128 + fr) * 128, boff = 32768 + (wc * 64 + fr) * 128, sw = fr & 7;
;     for (int kt = 0; kt < nk; ++kt) {
;         const int cur = (kt & 1) * 65536;
;         asm volatile("s_waitcnt vmcnt(0)" ::: "memory");
;         __syncthreads();
;         if (kt + 1 < nk) GLDS_STAGE(cur ^ 65536, kt + 1);
; #pragma unroll
;         for (int kh = 0; kh < 2; ++kh) {
;             bf16x8 bfr[4];
;             const int ch = ((kh * 4 + fq) ^ sw) << 4;
; #pragma unroll
;             for (int i = 0; i < 4; ++i) bfr[i] = *(const bf16x8*)(lds + cur + boff + i * 2048 + ch);
; #pragma unroll
;             for (int mh = 0; mh < 2; ++mh) {
;                 bf16x8 af[4];
; #pragma unroll
;                 for (int i = 0; i < 4; ++i) af[i] = *(const bf16x8*)(lds + cur + aoff + (mh * 4 + i) * 2048 + ch);
; #pragma unroll
;                 for (int mi = 0; mi < 4; ++mi)
; #pragma unroll
;                     for (int ni = 0; ni < 4; ++ni) acc[mh * 4 + mi][ni] = __builtin_amdgcn_mfma_f32_16x16x32_bf16(bfr[ni], af[mi], acc[mh * 4 + mi][ni], 0, 0, 0);
;             }
;         }
.Lg256r_c:
	s_and_b32 s48, s21, 0x10000
	s_xor_b32 s49, s48, 0x10000
	v_add_u32_e32 v206, s49, v138
	v_add_u32_e32 v207, s49, v150
	s_waitcnt vmcnt(0) lgkmcnt(0)
	s_barrier
	v_or_b32_e32 v248, s48, v153
	v_add_u32_e32 v249, s48, v151
	v_add_u32_e32 v244, v248, v152
	v_add_u32_e32 v245, v249, v152
	v_add_u32_e32 v246, v248, v149
	v_add_u32_e32 v247, v249, v149
	ds_read_b128 v[154:157], v244 offset:32768
	ds_read_b128 v[212:215], v245
	ds_read_b128 v[170:173], v244 offset:34816
	ds_read_b128 v[174:177], v244 offset:36864
	ds_read_b128 v[178:181], v244 offset:38912
	ds_read_b128 v[216:219], v245 offset:2048
	ds_read_b128 v[220:223], v245 offset:4096
	ds_read_b128 v[224:227], v245 offset:6144
	v_readfirstlane_b32 s40, v206
	v_readfirstlane_b32 s44, v207
	s_nop 0
	s_add_i32 s41, s40, 0x2000
	s_add_i32 s45, s44, 0x2000
	s_add_i32 s42, s40, 0x4000
	s_add_i32 s46, s44, 0x4000
	s_add_i32 s43, s40, 0x6000
	s_add_i32 s47, s44, 0x6000
	v_mfma_f32_16x16x32_bf16 v[62:65], v[182:185], v[228:231], v[62:65]
	s_mov_b32 m0, s40
	v_mfma_f32_16x16x32_bf16 v[58:61], v[186:189], v[228:231], v[58:61]
	global_load_lds_dwordx4 v[140:141], off
	v_mfma_f32_16x16x32_bf16 v[54:57], v[200:203], v[228:231], v[54:57]
	s_mov_b32 m0, s41
	v_lshl_add_u64 v[204:205], v[140:141], 0, s[4:5]
	v_mfma_f32_16x16x32_bf16 v[50:53], v[208:211], v[228:231], v[50:53]
	global_load_lds_dwordx4 v[204:205], off
	v_mfma_f32_16x16x32_bf16 v[46:49], v[182:185], v[232:235], v[46:49]
	s_mov_b32 m0, s42
	v_lshl_add_u64 v[204:205], v[140:141], 0, s[6:7]
	v_mfma_f32_16x16x32_bf16 v[42:45], v[186:189], v[232:235], v[42:45]
	global_load_lds_dwordx4 v[204:205], off
	v_mfma_f32_16x16x32_bf16 v[34:37], v[200:203], v[232:235], v[34:37]
	s_mov_b32 m0, s43
	v_lshl_add_u64 v[204:205], v[140:141], 0, s[8:9]
	v_mfma_f32_16x16x32_bf16 v[30:33], v[208:211], v[232:235], v[30:33]
	global_load_lds_dwordx4 v[204:205], off
	v_mfma_f32_16x16x32_bf16 v[26:29], v[182:185], v[236:239], v[26:29]
	s_mov_b32 m0, s44
	v_mfma_f32_16x16x32_bf16 v[22:25], v[186:189], v[236:239], v[22:25]
	global_load_lds_dwordx4 v[142:143], off
	v_mfma_f32_16x16x32_bf16 v[18:21], v[200:203], v[236:239], v[18:21]
	s_mov_b32 m0, s45
	v_lshl_add_u64 v[204:205], v[142:143], 0, s[4:5]
	v_mfma_f32_16x16x32_bf16 v[14:17], v[208:211], v[236:239], v[14:17]
	global_load_lds_dwordx4 v[204:205], off
	v_mfma_f32_16x16x32_bf16 v[10:13], v[182:185], v[240:243], v[10:13]
	s_mov_b32 m0, s46
	v_lshl_add_u64 v[204:205], v[142:143], 0, s[6:7]
	v_mfma_f32_16x16x32_bf16 v[6:9], v[186:189], v[240:243], v[6:9]
	global_load_lds_dwordx4 v[204:205], off
	v_mfma_f32_16x16x32_bf16 v[2:5], v[200:203], v[240:243], v[2:5]
	s_mov_b32 m0, s47
	v_lshl_add_u64 v[204:205], v[142:143], 0, s[8:9]
	v_mfma_f32_16x16x32_bf16 v[38:41], v[208:211], v[240:243], v[38:41]
	global_load_lds_dwordx4 v[204:205], off
	v_lshl_add_u64 v[140:141], v[140:141], 0, s[10:11]
	v_lshl_add_u64 v[142:143], v[142:143], 0, s[10:11]
	s_waitcnt lgkmcnt(6)
	v_mfma_f32_16x16x32_bf16 v[126:129], v[154:157], v[212:215], v[126:129]
	ds_read_b128 v[228:231], v245 offset:8192
	s_waitcnt lgkmcnt(6)
	v_mfma_f32_16x16x32_bf16 v[122:125], v[170:173], v[212:215], v[122:125]
	ds_read_b128 v[232:235], v245 offset:10240
	s_waitcnt lgkmcnt(6)
	v_mfma_f32_16x16x32_bf16 v[118:121], v[174:177], v[212:215], v[118:121]
	s_waitcnt lgkmcnt(5)
	v_mfma_f32_16x16x32_bf16 v[114:117], v[178:181], v[212:215], v[114:117]
	s_waitcnt lgkmcnt(4)
	v_mfma_f32_16x16x32_bf16 v[110:113], v[154:157], v[216:219], v[110:113]
	v_mfma_f32_16x16x32_bf16 v[106:109], v[170:173], v[216:219], v[106:109]
	v_mfma_f32_16x16x32_bf16 v[102:105], v[174:177], v[216:219], v[102:105]
	v_mfma_f32_16x16x32_bf16 v[98:101], v[178:181], v[216:219], v[98:101]
	s_waitcnt lgkmcnt(3)
	v_mfma_f32_16x16x32_bf16 v[94:97], v[154:157], v[220:223], v[94:97]
	ds_read_b128 v[236:239], v245 offset:12288
	v_mfma_f32_16x16x32_bf16 v[90:93], v[170:173], v[220:223], v[90:93]
	ds_read_b128 v[240:243], v245 offset:14336
	v_mfma_f32_16x16x32_bf16 v[86:89], v[174:177], v[220:223], v[86:89]
	v_mfma_f32_16x16x32_bf16 v[82:85], v[178:181], v[220:223], v[82:85]
	s_waitcnt lgkmcnt(4)
	v_mfma_f32_16x16x32_bf16 v[78:81], v[154:157], v[224:227], v[78:81]
	v_mfma_f32_16x16x32_bf16 v[74:77], v[170:173], v[224:227], v[74:77]
	v_mfma_f32_16x16x32_bf16 v[70:73], v[174:177], v[224:227], v[70:73]
	v_mfma_f32_16x16x32_bf16 v[66:69], v[178:181], v[224:227], v[66:69]
	s_waitcnt lgkmcnt(3)
	v_mfma_f32_16x16x32_bf16 v[62:65], v[154:157], v[228:231], v[62:65]
	ds_read_b128 v[182:185], v246 offset:32768
	v_mfma_f32_16x16x32_bf16 v[58:61], v[170:173], v[228:231], v[58:61]
	ds_read_b128 v[186:189], v246 offset:34816
	v_mfma_f32_16x16x32_bf16 v[54:57], v[174:177], v[228:231], v[54:57]
	ds_read_b128 v[200:203], v246 offset:36864
	v_mfma_f32_16x16x32_bf16 v[50:53], v[178:181], v[228:231], v[50:53]
	ds_read_b128 v[208:211], v246 offset:38912
	s_waitcnt lgkmcnt(6)
	v_mfma_f32_16x16x32_bf16 v[46:49], v[154:157], v[232:235], v[46:49]
	ds_read_b128 v[212:215], v247
	v_mfma_f32_16x16x32_bf16 v[42:45], v[170:173], v[232:235], v[42:45]
	ds_read_b128 v[216:219], v247 offset:2048
	v_mfma_f32_16x16x32_bf16 v[34:37], v[174:177], v[232:235], v[34:37]
	v_mfma_f32_16x16x32_bf16 v[30:33], v[178:181], v[232:235], v[30:33]
	s_waitcnt lgkmcnt(7)
	v_mfma_f32_16x16x32_bf16 v[26:29], v[154:157], v[236:239], v[26:29]
	ds_read_b128 v[220:223], v247 offset:4096
	v_mfma_f32_16x16x32_bf16 v[22:25], v[170:173], v[236:239], v[22:25]
	ds_read_b128 v[224:227], v247 offset:6144
	v_mfma_f32_16x16x32_bf16 v[18:21], v[174:177], v[236:239], v[18:21]
	v_mfma_f32_16x16x32_bf16 v[14:17], v[178:181], v[236:239], v[14:17]
	s_waitcnt lgkmcnt(8)
; #define GLDS_STAGE(st, kt_) do { \
;         _Pragma("unroll") for (int i_ = 0; i_ < FI; ++i_) { \
;             glds16(ap + (size_t)(32 * i_) * lda + (kt_) * 64, l3a + (st) + tid * 16 + i_ * 4096); \
;             glds16(bp + (size_t)(32 * i_) * ldb + (kt_) * 64, l3a + (st) + OPB + tid * 16 + i_ * 4096); } } while (0)
; #define GLDS_STAGE(st, kt_) do { \
;         _Pragma("unroll") for (int i_ = 0; i_ < 4; ++i_) { \
;             glds16(ap + (size_t)(64 * i_) * lda + (kt_) * 64, l3a + (st) + tid * 16 + i_ * 8192); \
;             glds16(bp + (size_t)(64 * i_) * ldb + (kt_) * 64, l3a + (st) + 32768 + tid * 16 + i_ * 8192); } } while (0)
; template <class Epi>
; DEV void gemm256_tile(const bf16_t* __restrict__ A, int lda, const bf16_t* __restrict__ Bt, int ldb, int K, unsigned char* lds, const Epi& epi) {
;     ...
;     for (int kt = 0; kt < nk; ++kt) {
;         const int cur = (kt & 1) * 65536;
;         asm volatile("s_waitcnt vmcnt(0)" ::: "memory");
;         __syncthreads();
;         if (kt + 1 < nk) GLDS_STAGE(cur ^ 65536, kt + 1);
; #pragma unroll
;         for (int kh = 0; kh < 2; ++kh) {
;             bf16x8 bfr[4];
;             const int ch = ((kh * 4 + fq) ^ sw) << 4;
; #pragma unroll
;             for (int i = 0; i < 4; ++i) bfr[i] = *(const bf16x8*)(lds + cur + boff + i * 2048 + ch);
; #pragma unroll
;             for (int mh = 0; mh < 2; ++mh) {
;                 bf16x8 af[4];
; #pragma unroll
;                 for (int i = 0; i < 4; ++i) af[i] = *(const bf16x8*)(lds + cur + aoff + (mh * 4 + i) * 2048 + ch);
; #pragma unroll
;                 for (int mi = 0; mi < 4; ++mi)
; #pragma unroll
;                     for (int ni = 0; ni < 4; ++ni) acc[mh * 4 + mi][ni] = __builtin_amdgcn_mfma_f32_16x16x32_bf16(bfr[ni], af[mi], acc[mh * 4 + mi][ni], 0, 0, 0);
;             }
;         }
	v_mfma_f32_16x16x32_bf16 v[10:13], v[154:157], v[240:243], v[10:13]
	v_mfma_f32_16x16x32_bf16 v[6:9], v[170:173], v[240:243], v[6:9]
	v_mfma_f32_16x16x32_bf16 v[2:5], v[174:177], v[240:243], v[2:5]
	v_mfma_f32_16x16x32_bf16 v[38:41], v[178:181], v[240:243], v[38:41]
	s_waitcnt lgkmcnt(3)
	v_mfma_f32_16x16x32_bf16 v[126:129], v[182:185], v[212:215], v[126:129]
	ds_read_b128 v[228:231], v247 offset:8192
	v_mfma_f32_16x16x32_bf16 v[122:125], v[186:189], v[212:215], v[122:125]
	ds_read_b128 v[232:235], v247 offset:10240
	v_mfma_f32_16x16x32_bf16 v[118:121], v[200:203], v[212:215], v[118:121]
	v_mfma_f32_16x16x32_bf16 v[114:117], v[208:211], v[212:215], v[114:117]
	s_waitcnt lgkmcnt(4)
	v_mfma_f32_16x16x32_bf16 v[110:113], v[182:185], v[216:219], v[110:113]
	v_mfma_f32_16x16x32_bf16 v[106:109], v[186:189], v[216:219], v[106:109]
	v_mfma_f32_16x16x32_bf16 v[102:105], v[200:203], v[216:219], v[102:105]
	v_mfma_f32_16x16x32_bf16 v[98:101], v[208:211], v[216:219], v[98:101]
	s_waitcnt lgkmcnt(3)
	v_mfma_f32_16x16x32_bf16 v[94:97], v[182:185], v[220:223], v[94:97]
	ds_read_b128 v[236:239], v247 offset:12288
	v_mfma_f32_16x16x32_bf16 v[90:93], v[186:189], v[220:223], v[90:93]
	ds_read_b128 v[240:243], v247 offset:14336
	v_mfma_f32_16x16x32_bf16 v[86:89], v[200:203], v[220:223], v[86:89]
	v_mfma_f32_16x16x32_bf16 v[82:85], v[208:211], v[220:223], v[82:85]
	s_waitcnt lgkmcnt(4)
	v_mfma_f32_16x16x32_bf16 v[78:81], v[182:185], v[224:227], v[78:81]
	v_mfma_f32_16x16x32_bf16 v[74:77], v[186:189], v[224:227], v[74:77]
	v_mfma_f32_16x16x32_bf16 v[70:73], v[200:203], v[224:227], v[70:73]
	v_mfma_f32_16x16x32_bf16 v[66:69], v[208:211], v[224:227], v[66:69]
	s_add_i32 s21, s21, 0x10000
	s_cmp_eq_u32 s21, 0x1f0000
	s_cbranch_scc0 .Lg256r_c
	s_waitcnt lgkmcnt(0)
	v_mfma_f32_16x16x32_bf16 v[62:65], v[182:185], v[228:231], v[62:65]
	v_mfma_f32_16x16x32_bf16 v[58:61], v[186:189], v[228:231], v[58:61]
	v_mfma_f32_16x16x32_bf16 v[54:57], v[200:203], v[228:231], v[54:57]
	v_mfma_f32_16x16x32_bf16 v[50:53], v[208:211], v[228:231], v[50:53]
	v_mfma_f32_16x16x32_bf16 v[46:49], v[182:185], v[232:235], v[46:49]
	v_mfma_f32_16x16x32_bf16 v[42:45], v[186:189], v[232:235], v[42:45]
	v_mfma_f32_16x16x32_bf16 v[34:37], v[200:203], v[232:235], v[34:37]
	v_mfma_f32_16x16x32_bf16 v[30:33], v[208:211], v[232:235], v[30:33]
	v_mfma_f32_16x16x32_bf16 v[26:29], v[182:185], v[236:239], v[26:29]
	v_mfma_f32_16x16x32_bf16 v[22:25], v[186:189], v[236:239], v[22:25]
	v_mfma_f32_16x16x32_bf16 v[18:21], v[200:203], v[236:239], v[18:21]
	v_mfma_f32_16x16x32_bf16 v[14:17], v[208:211], v[236:239], v[14:17]
	v_mfma_f32_16x16x32_bf16 v[10:13], v[182:185], v[240:243], v[10:13]
	v_mfma_f32_16x16x32_bf16 v[6:9], v[186:189], v[240:243], v[6:9]
	v_mfma_f32_16x16x32_bf16 v[2:5], v[200:203], v[240:243], v[2:5]
	v_mfma_f32_16x16x32_bf16 v[38:41], v[208:211], v[240:243], v[38:41]
	v_or_b32_e32 v186, 0x18000, v153
	v_add_u32_e32 v202, 0x10000, v151
	v_add_u32_e32 v174, v186, v152
	v_add_u32_e32 v182, v202, v152
	s_waitcnt vmcnt(0)
	s_barrier
	ds_read_b128 v[140:143], v174
	ds_read_b128 v[154:157], v174 offset:2048
	ds_read_b128 v[150:153], v182
	ds_read_b128 v[170:173], v174 offset:4096
	ds_read_b128 v[174:177], v174 offset:6144
	s_waitcnt lgkmcnt(2)
	v_mfma_f32_16x16x32_bf16 v[126:129], v[140:143], v[150:153], v[126:129]
	s_sext_i32_i8 s14, s20
	s_lshl_b32 s20, s14, 8
	s_ashr_i32 s21, s20, 31
	v_mfma_f32_16x16x32_bf16 v[122:125], v[154:157], v[150:153], v[122:125]
	s_waitcnt lgkmcnt(1)
	v_mfma_f32_16x16x32_bf16 v[118:121], v[170:173], v[150:153], v[118:121]
	s_waitcnt lgkmcnt(0)
	v_mfma_f32_16x16x32_bf16 v[114:117], v[174:177], v[150:153], v[114:117]
	ds_read_b128 v[150:153], v182 offset:2048
	s_waitcnt lgkmcnt(0)
	v_mfma_f32_16x16x32_bf16 v[110:113], v[140:143], v[150:153], v[110:113]
	v_mfma_f32_16x16x32_bf16 v[106:109], v[154:157], v[150:153], v[106:109]
	v_mfma_f32_16x16x32_bf16 v[102:105], v[170:173], v[150:153], v[102:105]
	v_mfma_f32_16x16x32_bf16 v[98:101], v[174:177], v[150:153], v[98:101]
	ds_read_b128 v[150:153], v182 offset:4096
	s_waitcnt lgkmcnt(0)
	v_mfma_f32_16x16x32_bf16 v[94:97], v[140:143], v[150:153], v[94:97]
	v_mfma_f32_16x16x32_bf16 v[90:93], v[154:157], v[150:153], v[90:93]
	v_mfma_f32_16x16x32_bf16 v[86:89], v[170:173], v[150:153], v[86:89]
	v_mfma_f32_16x16x32_bf16 v[82:85], v[174:177], v[150:153], v[82:85]
	ds_read_b128 v[150:153], v182 offset:6144
	s_waitcnt lgkmcnt(0)
	v_mfma_f32_16x16x32_bf16 v[78:81], v[140:143], v[150:153], v[78:81]
	v_mfma_f32_16x16x32_bf16 v[74:77], v[154:157], v[150:153], v[74:77]
	v_mfma_f32_16x16x32_bf16 v[70:73], v[170:173], v[150:153], v[70:73]
	v_mfma_f32_16x16x32_bf16 v[66:69], v[174:177], v[150:153], v[66:69]
	ds_read_b128 v[150:153], v182 offset:8192
	ds_read_b128 v[178:181], v182 offset:10240
	s_waitcnt lgkmcnt(1)
	v_mfma_f32_16x16x32_bf16 v[62:65], v[140:143], v[150:153], v[62:65]
	v_mfma_f32_16x16x32_bf16 v[58:61], v[154:157], v[150:153], v[58:61]
	v_mfma_f32_16x16x32_bf16 v[54:57], v[170:173], v[150:153], v[54:57]
	v_mfma_f32_16x16x32_bf16 v[50:53], v[174:177], v[150:153], v[50:53]
	ds_read_b128 v[150:153], v182 offset:12288
	s_waitcnt lgkmcnt(1)
	v_mfma_f32_16x16x32_bf16 v[46:49], v[140:143], v[178:181], v[46:49]
	v_mfma_f32_16x16x32_bf16 v[42:45], v[154:157], v[178:181], v[42:45]
	v_mfma_f32_16x16x32_bf16 v[34:37], v[170:173], v[178:181], v[34:37]
	v_mfma_f32_16x16x32_bf16 v[30:33], v[174:177], v[178:181], v[30:33]
	ds_read_b128 v[178:181], v182 offset:14336
	s_waitcnt lgkmcnt(1)
; DEV unsigned cvt_pk_bf16(float lo, float hi) { const f32x2_t v = {lo, hi}; const bf16x2_t b = __builtin_convertvector(v, bf16x2_t); return __builtin_bit_cast(unsigned, b); }
; template <class Epi>
; DEV void gemm256_tile(const bf16_t* __restrict__ A, int lda, const bf16_t* __restrict__ Bt, int ldb, int K, unsigned char* lds, const Epi& epi) {
;     ...
; #pragma unroll
;         for (int kh = 0; kh < 2; ++kh) {
;             bf16x8 bfr[4];
;             const int ch = ((kh * 4 + fq) ^ sw) << 4;
; #pragma unroll
;             for (int i = 0; i < 4; ++i) bfr[i] = *(const bf16x8*)(lds + cur + boff + i * 2048 + ch);
; #pragma unroll
;             for (int mh = 0; mh < 2; ++mh) {
;                 bf16x8 af[4];
; #pragma unroll
;                 for (int i = 0; i < 4; ++i) af[i] = *(const bf16x8*)(lds + cur + aoff + (mh * 4 + i) * 2048 + ch);
; #pragma unroll
;                 for (int mi = 0; mi < 4; ++mi)
; #pragma unroll
;                     for (int ni = 0; ni < 4; ++ni) acc[mh * 4 + mi][ni] = __builtin_amdgcn_mfma_f32_16x16x32_bf16(bfr[ni], af[mi], acc[mh * 4 + mi][ni], 0, 0, 0);
;             }
;     ...
; #pragma unroll
;         for (int mi = 0; mi < 8; ++mi)
; #pragma unroll
;             for (int ni = 0; ni < 4; ++ni) {
;                 const int row = wr * 128 + mi * 16 + fr, col = wc * 64 + ni * 16 + fq * 4;
;                 const f32x4 v = epi.xform(row, col, acc[mi][ni]);
;                 uint2 w; w.x = cvt_pk_bf16(v[0], v[1]); w.y = cvt_pk_bf16(v[2], v[3]);
;                 *(uint2*)(lds + row * 512 + ((((col >> 3) ^ (row & 31)) << 4) | (((col >> 2) & 1) << 3))) = w;
	v_mfma_f32_16x16x32_bf16 v[182:185], v[140:143], v[150:153], v[26:29]
	s_nop 2
	v_add_u32_e32 v29, v186, v149
	ds_read_b128 v[186:189], v29
	ds_read_b128 v[190:193], v29 offset:2048
	ds_read_b128 v[194:197], v29 offset:4096
	ds_read_b128 v[198:201], v29 offset:6144
	v_add_u32_e32 v29, v202, v149
	v_mfma_f32_16x16x32_bf16 v[22:25], v[154:157], v[150:153], v[22:25]
	v_and_b32_e32 v28, 0xc0, v144
	v_lshl_or_b32 v147, v147, 2, v28
	v_lshlrev_b32_e32 v28, 3, v146
	v_mfma_f32_16x16x32_bf16 v[18:21], v[170:173], v[150:153], v[18:21]
	v_lshl_add_u64 v[26:27], v[132:133], 0, s[12:13]
	v_lshl_add_u64 v[26:27], s[20:21], 1, v[26:27]
	s_mov_b32 s12, 0
	v_mfma_f32_16x16x32_bf16 v[14:17], v[174:177], v[150:153], v[14:17]
	ds_read_b128 v[150:153], v29
	ds_read_b128 v[202:205], v29 offset:2048
	ds_read_b128 v[206:209], v29 offset:4096
	ds_read_b128 v[210:213], v29 offset:6144
	s_waitcnt lgkmcnt(3)
	v_mfma_f32_16x16x32_bf16 v[126:129], v[186:189], v[150:153], v[126:129]
	v_mfma_f32_16x16x32_bf16 v[122:125], v[190:193], v[150:153], v[122:125]
	s_waitcnt lgkmcnt(1)
	v_mfma_f32_16x16x32_bf16 v[94:97], v[186:189], v[206:209], v[94:97]
	v_mfma_f32_16x16x32_bf16 v[10:13], v[140:143], v[178:181], v[10:13]
	ds_read_b128 v[140:143], v29 offset:8192
	ds_read_b128 v[214:217], v29 offset:10240
	ds_read_b128 v[218:221], v29 offset:12288
	ds_read_b128 v[222:225], v29 offset:14336
	v_lshlrev_b32_e32 v29, 9, v148
	v_and_or_b32 v146, v28, 8, v29
	v_mfma_f32_16x16x32_bf16 v[118:121], v[194:197], v[150:153], v[118:121]
	v_cvt_pk_bf16_f32 v28, v126, v127
	v_lshrrev_b32_e32 v126, 3, v147
	v_xor_b32_e32 v127, v126, v145
	v_mfma_f32_16x16x32_bf16 v[90:93], v[190:193], v[206:209], v[90:93]
	v_cvt_pk_bf16_f32 v29, v128, v129
	v_lshl_or_b32 v127, v127, 4, v146
	v_cvt_pk_bf16_f32 v122, v122, v123
	v_mfma_f32_16x16x32_bf16 v[114:117], v[198:201], v[150:153], v[114:117]
	v_cvt_pk_bf16_f32 v123, v124, v125
	v_bitop3_b32 v124, v126, v145, 2 bitop3:0x36
	v_cvt_pk_bf16_f32 v94, v94, v95
	v_mfma_f32_16x16x32_bf16 v[86:89], v[194:197], v[206:209], v[86:89]
	v_cvt_pk_bf16_f32 v95, v96, v97
	s_waitcnt lgkmcnt(0)
	s_barrier
; DEV unsigned cvt_pk_bf16(float lo, float hi) { const f32x2_t v = {lo, hi}; const bf16x2_t b = __builtin_convertvector(v, bf16x2_t); return __builtin_bit_cast(unsigned, b); }
; template <class Epi>
; DEV void gemm256_tile(const bf16_t* __restrict__ A, int lda, const bf16_t* __restrict__ Bt, int ldb, int K, unsigned char* lds, const Epi& epi) {
;     ...
; #pragma unroll
;         for (int mi = 0; mi < 8; ++mi)
; #pragma unroll
;             for (int ni = 0; ni < 4; ++ni) {
;                 const int row = wr * 128 + mi * 16 + fr, col = wc * 64 + ni * 16 + fq * 4;
;                 const f32x4 v = epi.xform(row, col, acc[mi][ni]);
;                 uint2 w; w.x = cvt_pk_bf16(v[0], v[1]); w.y = cvt_pk_bf16(v[2], v[3]);
;                 *(uint2*)(lds + row * 512 + ((((col >> 3) ^ (row & 31)) << 4) | (((col >> 2) & 1) << 3))) = w;
;             }
;         __syncthreads();
	v_mfma_f32_16x16x32_bf16 v[110:113], v[186:189], v[202:205], v[110:113]
	v_lshl_add_u32 v124, v124, 4, v146
	v_cvt_pk_bf16_f32 v118, v118, v119
	v_mfma_f32_16x16x32_bf16 v[82:85], v[198:201], v[206:209], v[82:85]
	v_cvt_pk_bf16_f32 v119, v120, v121
	v_bitop3_b32 v120, v126, v145, 4 bitop3:0x36
	ds_write2st64_b64 v127, v[28:29], v[94:95] offset1:32
	v_mfma_f32_16x16x32_bf16 v[106:109], v[190:193], v[202:205], v[106:109]
	v_cvt_pk_bf16_f32 v28, v90, v91
	v_cvt_pk_bf16_f32 v29, v92, v93
	v_lshl_add_u32 v120, v120, 4, v146
	v_mfma_f32_16x16x32_bf16 v[78:81], v[186:189], v[210:213], v[78:81]
	v_cvt_pk_bf16_f32 v114, v114, v115
	v_cvt_pk_bf16_f32 v115, v116, v117
	v_bitop3_b32 v116, v126, v145, 6 bitop3:0x36
	v_mfma_f32_16x16x32_bf16 v[102:105], v[194:197], v[202:205], v[102:105]
	ds_write2st64_b64 v124, v[122:123], v[28:29] offset1:32
	v_cvt_pk_bf16_f32 v28, v86, v87
	v_cvt_pk_bf16_f32 v29, v88, v89
	v_mfma_f32_16x16x32_bf16 v[74:77], v[190:193], v[210:213], v[74:77]
	v_lshl_add_u32 v116, v116, 4, v146
	v_or_b32_e32 v117, 16, v145
	v_cvt_pk_bf16_f32 v110, v110, v111
	v_mfma_f32_16x16x32_bf16 v[2:5], v[170:173], v[178:181], v[2:5]
	v_cvt_pk_bf16_f32 v111, v112, v113
	v_bitop3_b32 v112, v126, v145, 16 bitop3:0x1e
	ds_write2st64_b64 v120, v[118:119], v[28:29] offset1:32
	v_mfma_f32_16x16x32_bf16 v[98:101], v[198:201], v[202:205], v[98:101]
	v_cvt_pk_bf16_f32 v28, v82, v83
	v_cvt_pk_bf16_f32 v29, v84, v85
	v_lshl_or_b32 v112, v112, 4, v146
	v_mfma_f32_16x16x32_bf16 v[70:73], v[194:197], v[210:213], v[70:73]
	v_cvt_pk_bf16_f32 v106, v106, v107
	v_cvt_pk_bf16_f32 v107, v108, v109
	v_bitop3_b32 v108, v126, v117, 2 bitop3:0x36
	v_mfma_f32_16x16x32_bf16 v[66:69], v[198:201], v[210:213], v[66:69]
	ds_write2st64_b64 v116, v[114:115], v[28:29] offset1:32
	v_cvt_pk_bf16_f32 v28, v78, v79
	v_cvt_pk_bf16_f32 v29, v80, v81
	v_lshl_add_u32 v108, v108, 4, v146
	v_cvt_pk_bf16_f32 v102, v102, v103
	v_cvt_pk_bf16_f32 v103, v104, v105
	v_bitop3_b32 v104, v126, v117, 4 bitop3:0x36
	ds_write2st64_b64 v112, v[110:111], v[28:29] offset0:16 offset1:48
	v_cvt_pk_bf16_f32 v28, v74, v75
	v_cvt_pk_bf16_f32 v29, v76, v77
	v_lshl_add_u32 v104, v104, 4, v146
	v_cvt_pk_bf16_f32 v98, v98, v99
	v_cvt_pk_bf16_f32 v99, v100, v101
	v_bitop3_b32 v100, v126, v117, 6 bitop3:0x36
	ds_write2st64_b64 v108, v[106:107], v[28:29] offset0:16 offset1:48
	v_cvt_pk_bf16_f32 v28, v70, v71
	v_cvt_pk_bf16_f32 v29, v72, v73
	v_mfma_f32_16x16x32_bf16 v[34:37], v[194:197], v[214:217], v[34:37]
	v_lshl_add_u32 v100, v100, 4, v146
	ds_write2st64_b64 v104, v[102:103], v[28:29] offset0:16 offset1:48
	v_cvt_pk_bf16_f32 v28, v66, v67
	v_mfma_f32_16x16x32_bf16 v[2:5], v[194:197], v[222:225], v[2:5]
	v_cvt_pk_bf16_f32 v29, v68, v69
	ds_write2st64_b64 v100, v[98:99], v[28:29] offset0:16 offset1:48
	s_nop 1
	v_cvt_pk_bf16_f32 v34, v34, v35
	v_mfma_f32_16x16x32_bf16 v[38:41], v[174:177], v[178:181], v[38:41]
	v_cvt_pk_bf16_f32 v35, v36, v37
	s_nop 0
	v_cvt_pk_bf16_f32 v2, v2, v3
	v_cvt_pk_bf16_f32 v3, v4, v5
	v_mfma_f32_16x16x32_bf16 v[6:9], v[154:157], v[178:181], v[6:9]
	ds_write2st64_b64 v104, v[34:35], v[2:3] offset0:80 offset1:112
	v_mfma_f32_16x16x32_bf16 v[28:31], v[198:201], v[214:217], v[30:33]
	v_mfma_f32_16x16x32_bf16 v[2:5], v[198:201], v[222:225], v[38:41]
	v_mfma_f32_16x16x32_bf16 v[62:65], v[186:189], v[140:143], v[62:65]
	s_nop 5
	v_cvt_pk_bf16_f32 v32, v28, v29
	v_cvt_pk_bf16_f32 v33, v30, v31
	v_cvt_pk_bf16_f32 v2, v2, v3
	v_mfma_f32_16x16x32_bf16 v[58:61], v[190:193], v[140:143], v[58:61]
	v_cvt_pk_bf16_f32 v3, v4, v5
	v_cvt_pk_bf16_f32 v62, v62, v63
	v_cvt_pk_bf16_f32 v63, v64, v65
	v_mfma_f32_16x16x32_bf16 v[54:57], v[194:197], v[140:143], v[54:57]
	ds_write2st64_b64 v100, v[32:33], v[2:3] offset0:80 offset1:112
	s_nop 2
	v_cvt_pk_bf16_f32 v58, v58, v59
	v_cvt_pk_bf16_f32 v59, v60, v61
	v_mfma_f32_16x16x32_bf16 v[50:53], v[198:201], v[140:143], v[50:53]
	v_and_b32_e32 v2, 0x1f0, v138
	v_cvt_pk_bf16_f32 v54, v54, v55
	v_cvt_pk_bf16_f32 v55, v56, v57
	v_mfma_f32_16x16x32_bf16 v[46:49], v[186:189], v[214:217], v[46:49]
	v_mfma_f32_16x16x32_bf16 v[42:45], v[190:193], v[214:217], v[42:45]
	s_nop 2
	v_cvt_pk_bf16_f32 v50, v50, v51
	v_cvt_pk_bf16_f32 v51, v52, v53
	s_nop 1
	v_cvt_pk_bf16_f32 v46, v46, v47
	v_mfma_f32_16x16x32_bf16 v[28:31], v[186:189], v[218:221], v[182:185]
	v_cvt_pk_bf16_f32 v47, v48, v49
	v_cvt_pk_bf16_f32 v42, v42, v43
	v_cvt_pk_bf16_f32 v43, v44, v45
	v_mfma_f32_16x16x32_bf16 v[22:25], v[190:193], v[218:221], v[22:25]
	v_mfma_f32_16x16x32_bf16 v[18:21], v[194:197], v[218:221], v[18:21]
	s_nop 2
	v_cvt_pk_bf16_f32 v28, v28, v29
	v_cvt_pk_bf16_f32 v29, v30, v31
	s_nop 1
	v_cvt_pk_bf16_f32 v22, v22, v23
	v_mfma_f32_16x16x32_bf16 v[14:17], v[198:201], v[218:221], v[14:17]
	v_cvt_pk_bf16_f32 v23, v24, v25
	v_cvt_pk_bf16_f32 v18, v18, v19
	v_cvt_pk_bf16_f32 v19, v20, v21
	v_mfma_f32_16x16x32_bf16 v[10:13], v[186:189], v[222:225], v[10:13]
	ds_write2st64_b64 v127, v[62:63], v[28:29] offset0:64 offset1:96
	s_nop 2
	v_cvt_pk_bf16_f32 v14, v14, v15
	v_cvt_pk_bf16_f32 v15, v16, v17
	v_mfma_f32_16x16x32_bf16 v[6:9], v[190:193], v[222:225], v[6:9]
	ds_write2st64_b64 v124, v[58:59], v[22:23] offset0:64 offset1:96
	v_cvt_pk_bf16_f32 v10, v10, v11
	v_cvt_pk_bf16_f32 v11, v12, v13
	ds_write2st64_b64 v120, v[54:55], v[18:19] offset0:64 offset1:96
	ds_write2st64_b64 v116, v[50:51], v[14:15] offset0:64 offset1:96
	s_nop 2
	v_cvt_pk_bf16_f32 v6, v6, v7
	v_cvt_pk_bf16_f32 v7, v8, v9
	ds_write2st64_b64 v112, v[46:47], v[10:11] offset0:80 offset1:112
	ds_write2st64_b64 v108, v[42:43], v[6:7] offset0:80 offset1:112
	s_waitcnt lgkmcnt(0)
	s_barrier

; #define GLDS_STAGE(st, kt_) do { \
;         _Pragma("unroll") for (int i_ = 0; i_ < FI; ++i_) { \
;             glds16(ap + (size_t)(32 * i_) * lda + (kt_) * 64, l3a + (st) + tid * 16 + i_ * 4096); \
;             glds16(bp + (size_t)(32 * i_) * ldb + (kt_) * 64, l3a + (st) + OPB + tid * 16 + i_ * 4096); } } while (0)
; #define GLDS_STAGE(st, kt_) do { \
;         _Pragma("unroll") for (int i_ = 0; i_ < 4; ++i_) { \
;             glds16(ap + (size_t)(64 * i_) * lda + (kt_) * 64, l3a + (st) + tid * 16 + i_ * 8192); \
;             glds16(bp + (size_t)(64 * i_) * ldb + (kt_) * 64, l3a + (st) + 32768 + tid * 16 + i_ * 8192); } } while (0)
; template <class Epi>
; DEV void gemm256_tile(const bf16_t* __restrict__ A, int lda, const bf16_t* __restrict__ Bt, int ldb, int K, unsigned char* lds, const Epi& epi) {
;     ...
;     GLDS_STAGE(0, 0);
;     const int aoff = (wr * 128 + fr) * 128, boff = 32768 + (wc * 64 + fr) * 128, sw = fr & 7;
;     for (int kt = 0; kt < nk; ++kt) {
;         const int cur = (kt & 1) * 65536;
;         asm volatile("s_waitcnt vmcnt(0)" ::: "memory");
;         __syncthreads();
;         if (kt + 1 < nk) GLDS_STAGE(cur ^ 65536, kt + 1);
; #pragma unroll
;         for (int kh = 0; kh < 2; ++kh) {
;             bf16x8 bfr[4];
;             const int ch = ((kh * 4 + fq) ^ sw) << 4;
; #pragma unroll
;             for (int i = 0; i < 4; ++i) bfr[i] = *(const bf16x8*)(lds + cur + boff + i * 2048 + ch);
; #pragma unroll
;             for (int mh = 0; mh < 2; ++mh) {
;                 bf16x8 af[4];
; #pragma unroll
;                 for (int i = 0; i < 4; ++i) af[i] = *(const bf16x8*)(lds + cur + aoff + (mh * 4 + i) * 2048 + ch);
; #pragma unroll
;                 for (int mi = 0; mi < 4; ++mi)
; #pragma unroll
;                     for (int ni = 0; ni < 4; ++ni) acc[mh * 4 + mi][ni] = __builtin_amdgcn_mfma_f32_16x16x32_bf16(bfr[ni], af[mi], acc[mh * 4 + mi][ni], 0, 0, 0);
;             }
;         }
.LBB0_1466:
	s_and_b32 s48, s21, 0x10000
	s_xor_b32 s49, s48, 0x10000
	v_add_u32_e32 v206, s49, v140
	v_add_u32_e32 v207, s49, v153
	s_waitcnt vmcnt(0) lgkmcnt(0)
	s_barrier
	v_or_b32_e32 v248, s48, v155
	v_add_u32_e32 v249, s48, v152
	v_add_u32_e32 v244, v248, v154
	v_add_u32_e32 v245, v249, v154
	v_add_u32_e32 v246, v248, v151
	v_add_u32_e32 v247, v249, v151
	ds_read_b128 v[162:165], v244 offset:32768
	ds_read_b128 v[212:215], v245
	ds_read_b128 v[166:169], v244 offset:34816
	ds_read_b128 v[170:173], v244 offset:36864
	ds_read_b128 v[174:177], v244 offset:38912
	ds_read_b128 v[216:219], v245 offset:2048
	ds_read_b128 v[220:223], v245 offset:4096
	ds_read_b128 v[224:227], v245 offset:6144
	v_readfirstlane_b32 s40, v206
	v_readfirstlane_b32 s44, v207
	s_nop 0
	s_add_i32 s41, s40, 0x2000
	s_add_i32 s45, s44, 0x2000
	s_add_i32 s42, s40, 0x4000
	s_add_i32 s46, s44, 0x4000
	s_add_i32 s43, s40, 0x6000
	s_add_i32 s47, s44, 0x6000
	s_waitcnt lgkmcnt(6)
	v_mfma_f32_16x16x32_bf16 v[126:129], v[162:165], v[212:215], v[126:129]
	ds_read_b128 v[228:231], v245 offset:8192
	s_waitcnt lgkmcnt(6)
	v_mfma_f32_16x16x32_bf16 v[122:125], v[166:169], v[212:215], v[122:125]
	ds_read_b128 v[232:235], v245 offset:10240
	s_waitcnt lgkmcnt(6)
	v_mfma_f32_16x16x32_bf16 v[118:121], v[170:173], v[212:215], v[118:121]
	s_mov_b32 m0, s40
	s_waitcnt lgkmcnt(5)
	v_mfma_f32_16x16x32_bf16 v[114:117], v[174:177], v[212:215], v[114:117]
	global_load_lds_dwordx4 v[142:143], off
	s_waitcnt lgkmcnt(4)
	v_mfma_f32_16x16x32_bf16 v[110:113], v[162:165], v[216:219], v[110:113]
	s_mov_b32 m0, s41
	v_lshl_add_u64 v[204:205], v[142:143], 0, s[4:5]
	v_mfma_f32_16x16x32_bf16 v[106:109], v[166:169], v[216:219], v[106:109]
	global_load_lds_dwordx4 v[204:205], off
	v_mfma_f32_16x16x32_bf16 v[102:105], v[170:173], v[216:219], v[102:105]
	s_mov_b32 m0, s42
	v_lshl_add_u64 v[204:205], v[142:143], 0, s[6:7]
	v_mfma_f32_16x16x32_bf16 v[98:101], v[174:177], v[216:219], v[98:101]
	global_load_lds_dwordx4 v[204:205], off
	s_waitcnt lgkmcnt(3)
	v_mfma_f32_16x16x32_bf16 v[94:97], v[162:165], v[220:223], v[94:97]
	ds_read_b128 v[236:239], v245 offset:12288
	v_mfma_f32_16x16x32_bf16 v[90:93], v[166:169], v[220:223], v[90:93]
	ds_read_b128 v[240:243], v245 offset:14336
	v_mfma_f32_16x16x32_bf16 v[86:89], v[170:173], v[220:223], v[86:89]
	s_mov_b32 m0, s43
	v_lshl_add_u64 v[204:205], v[142:143], 0, s[8:9]
	v_mfma_f32_16x16x32_bf16 v[82:85], v[174:177], v[220:223], v[82:85]
	global_load_lds_dwordx4 v[204:205], off
	s_waitcnt lgkmcnt(4)
	v_mfma_f32_16x16x32_bf16 v[78:81], v[162:165], v[224:227], v[78:81]
	s_mov_b32 m0, s44
	v_mfma_f32_16x16x32_bf16 v[74:77], v[166:169], v[224:227], v[74:77]
	global_load_lds_dwordx4 v[144:145], off
	v_mfma_f32_16x16x32_bf16 v[70:73], v[170:173], v[224:227], v[70:73]
	s_mov_b32 m0, s45
	v_lshl_add_u64 v[204:205], v[144:145], 0, s[4:5]
	v_mfma_f32_16x16x32_bf16 v[66:69], v[174:177], v[224:227], v[66:69]
	global_load_lds_dwordx4 v[204:205], off
	s_waitcnt lgkmcnt(3)
	v_mfma_f32_16x16x32_bf16 v[62:65], v[162:165], v[228:231], v[62:65]
	ds_read_b128 v[178:181], v246 offset:32768
	v_mfma_f32_16x16x32_bf16 v[58:61], v[166:169], v[228:231], v[58:61]
	ds_read_b128 v[182:185], v246 offset:34816
	v_mfma_f32_16x16x32_bf16 v[54:57], v[170:173], v[228:231], v[54:57]
	ds_read_b128 v[200:203], v246 offset:36864
	v_mfma_f32_16x16x32_bf16 v[50:53], v[174:177], v[228:231], v[50:53]
	ds_read_b128 v[208:211], v246 offset:38912
	s_waitcnt lgkmcnt(6)
	v_mfma_f32_16x16x32_bf16 v[46:49], v[162:165], v[232:235], v[46:49]
	ds_read_b128 v[212:215], v247
	v_mfma_f32_16x16x32_bf16 v[42:45], v[166:169], v[232:235], v[42:45]
	ds_read_b128 v[216:219], v247 offset:2048
	v_mfma_f32_16x16x32_bf16 v[34:37], v[170:173], v[232:235], v[34:37]
	s_mov_b32 m0, s46
	v_lshl_add_u64 v[204:205], v[144:145], 0, s[6:7]
	v_mfma_f32_16x16x32_bf16 v[30:33], v[174:177], v[232:235], v[30:33]
	global_load_lds_dwordx4 v[204:205], off
	s_mov_b32 m0, s47
	v_lshl_add_u64 v[204:205], v[144:145], 0, s[8:9]
	global_load_lds_dwordx4 v[204:205], off
	v_lshl_add_u64 v[142:143], v[142:143], 0, s[10:11]
	v_lshl_add_u64 v[144:145], v[144:145], 0, s[10:11]
	s_waitcnt lgkmcnt(7)
	v_mfma_f32_16x16x32_bf16 v[26:29], v[162:165], v[236:239], v[26:29]
	ds_read_b128 v[220:223], v247 offset:4096
	v_mfma_f32_16x16x32_bf16 v[22:25], v[166:169], v[236:239], v[22:25]
	ds_read_b128 v[224:227], v247 offset:6144
	v_mfma_f32_16x16x32_bf16 v[18:21], v[170:173], v[236:239], v[18:21]
	v_mfma_f32_16x16x32_bf16 v[14:17], v[174:177], v[236:239], v[14:17]
	s_waitcnt lgkmcnt(8)
	v_mfma_f32_16x16x32_bf16 v[10:13], v[162:165], v[240:243], v[10:13]
	v_mfma_f32_16x16x32_bf16 v[6:9], v[166:169], v[240:243], v[6:9]
	v_mfma_f32_16x16x32_bf16 v[2:5], v[170:173], v[240:243], v[2:5]
	v_mfma_f32_16x16x32_bf16 v[38:41], v[174:177], v[240:243], v[38:41]
	s_waitcnt lgkmcnt(3)
	v_mfma_f32_16x16x32_bf16 v[126:129], v[178:181], v[212:215], v[126:129]
	ds_read_b128 v[228:231], v247 offset:8192
	v_mfma_f32_16x16x32_bf16 v[122:125], v[182:185], v[212:215], v[122:125]
	ds_read_b128 v[232:235], v247 offset:10240
	v_mfma_f32_16x16x32_bf16 v[118:121], v[200:203], v[212:215], v[118:121]
	v_mfma_f32_16x16x32_bf16 v[114:117], v[208:211], v[212:215], v[114:117]
	s_waitcnt lgkmcnt(4)
	v_mfma_f32_16x16x32_bf16 v[110:113], v[178:181], v[216:219], v[110:113]
	v_mfma_f32_16x16x32_bf16 v[106:109], v[182:185], v[216:219], v[106:109]
	v_mfma_f32_16x16x32_bf16 v[102:105], v[200:203], v[216:219], v[102:105]
	v_mfma_f32_16x16x32_bf16 v[98:101], v[208:211], v[216:219], v[98:101]
	s_waitcnt lgkmcnt(3)
	v_mfma_f32_16x16x32_bf16 v[94:97], v[178:181], v[220:223], v[94:97]
	ds_read_b128 v[236:239], v247 offset:12288
	v_mfma_f32_16x16x32_bf16 v[90:93], v[182:185], v[220:223], v[90:93]
	ds_read_b128 v[240:243], v247 offset:14336
	v_mfma_f32_16x16x32_bf16 v[86:89], v[200:203], v[220:223], v[86:89]
	v_mfma_f32_16x16x32_bf16 v[82:85], v[208:211], v[220:223], v[82:85]
	s_waitcnt lgkmcnt(4)
	v_mfma_f32_16x16x32_bf16 v[78:81], v[178:181], v[224:227], v[78:81]
	v_mfma_f32_16x16x32_bf16 v[74:77], v[182:185], v[224:227], v[74:77]
	v_mfma_f32_16x16x32_bf16 v[70:73], v[200:203], v[224:227], v[70:73]
	v_mfma_f32_16x16x32_bf16 v[66:69], v[208:211], v[224:227], v[66:69]
	s_add_i32 s21, s21, 0x10000
; #define GLDS_STAGE(st, kt_) do { \
;         _Pragma("unroll") for (int i_ = 0; i_ < FI; ++i_) { \
;             glds16(ap + (size_t)(32 * i_) * lda + (kt_) * 64, l3a + (st) + tid * 16 + i_ * 4096); \
;             glds16(bp + (size_t)(32 * i_) * ldb + (kt_) * 64, l3a + (st) + OPB + tid * 16 + i_ * 4096); } } while (0)
; #define GLDS_STAGE(st, kt_) do { \
;         _Pragma("unroll") for (int i_ = 0; i_ < 4; ++i_) { \
;             glds16(ap + (size_t)(64 * i_) * lda + (kt_) * 64, l3a + (st) + tid * 16 + i_ * 8192); \
;             glds16(bp + (size_t)(64 * i_) * ldb + (kt_) * 64, l3a + (st) + 32768 + tid * 16 + i_ * 8192); } } while (0)
; template <class Epi>
; DEV void gemm256_tile(const bf16_t* __restrict__ A, int lda, const bf16_t* __restrict__ Bt, int ldb, int K, unsigned char* lds, const Epi& epi) {
;     ...
;     GLDS_STAGE(0, 0);
;     const int aoff = (wr * 128 + fr) * 128, boff = 32768 + (wc * 64 + fr) * 128, sw = fr & 7;
;     for (int kt = 0; kt < nk; ++kt) {
;         const int cur = (kt & 1) * 65536;
;         asm volatile("s_waitcnt vmcnt(0)" ::: "memory");
;         __syncthreads();
;         if (kt + 1 < nk) GLDS_STAGE(cur ^ 65536, kt + 1);
; #pragma unroll
;         for (int kh = 0; kh < 2; ++kh) {
;             bf16x8 bfr[4];
;             const int ch = ((kh * 4 + fq) ^ sw) << 4;
; #pragma unroll
;             for (int i = 0; i < 4; ++i) bfr[i] = *(const bf16x8*)(lds + cur + boff + i * 2048 + ch);
; #pragma unroll
;             for (int mh = 0; mh < 2; ++mh) {
;                 bf16x8 af[4];
; #pragma unroll
;                 for (int i = 0; i < 4; ++i) af[i] = *(const bf16x8*)(lds + cur + aoff + (mh * 4 + i) * 2048 + ch);
; #pragma unroll
;                 for (int mi = 0; mi < 4; ++mi)
; #pragma unroll
;                     for (int ni = 0; ni < 4; ++ni) acc[mh * 4 + mi][ni] = __builtin_amdgcn_mfma_f32_16x16x32_bf16(bfr[ni], af[mi], acc[mh * 4 + mi][ni], 0, 0, 0);
.Lg256r_d:
	s_and_b32 s48, s21, 0x10000
	s_xor_b32 s49, s48, 0x10000
	v_add_u32_e32 v206, s49, v140
	v_add_u32_e32 v207, s49, v153
	s_waitcnt vmcnt(0) lgkmcnt(0)
	s_barrier
	v_or_b32_e32 v248, s48, v155
	v_add_u32_e32 v249, s48, v152
	v_add_u32_e32 v244, v248, v154
	v_add_u32_e32 v245, v249, v154
	v_add_u32_e32 v246, v248, v151
	v_add_u32_e32 v247, v249, v151
	ds_read_b128 v[162:165], v244 offset:32768
	ds_read_b128 v[212:215], v245
	ds_read_b128 v[166:169], v244 offset:34816
	ds_read_b128 v[170:173], v244 offset:36864
	ds_read_b128 v[174:177], v244 offset:38912
	ds_read_b128 v[216:219], v245 offset:2048
	ds_read_b128 v[220:223], v245 offset:4096
	ds_read_b128 v[224:227], v245 offset:6144
	v_readfirstlane_b32 s40, v206
	v_readfirstlane_b32 s44, v207
	s_nop 0
	s_add_i32 s41, s40, 0x2000
	s_add_i32 s45, s44, 0x2000
	s_add_i32 s42, s40, 0x4000
	s_add_i32 s46, s44, 0x4000
	s_add_i32 s43, s40, 0x6000
	s_add_i32 s47, s44, 0x6000
	v_mfma_f32_16x16x32_bf16 v[62:65], v[178:181], v[228:231], v[62:65]
	s_mov_b32 m0, s40
	v_mfma_f32_16x16x32_bf16 v[58:61], v[182:185], v[228:231], v[58:61]
	global_load_lds_dwordx4 v[142:143], off
	v_mfma_f32_16x16x32_bf16 v[54:57], v[200:203], v[228:231], v[54:57]
	s_mov_b32 m0, s41
	v_lshl_add_u64 v[204:205], v[142:143], 0, s[4:5]
	v_mfma_f32_16x16x32_bf16 v[50:53], v[208:211], v[228:231], v[50:53]
	global_load_lds_dwordx4 v[204:205], off
	v_mfma_f32_16x16x32_bf16 v[46:49], v[178:181], v[232:235], v[46:49]
	s_mov_b32 m0, s42
	v_lshl_add_u64 v[204:205], v[142:143], 0, s[6:7]
	v_mfma_f32_16x16x32_bf16 v[42:45], v[182:185], v[232:235], v[42:45]
	global_load_lds_dwordx4 v[204:205], off
	v_mfma_f32_16x16x32_bf16 v[34:37], v[200:203], v[232:235], v[34:37]
	s_mov_b32 m0, s43
	v_lshl_add_u64 v[204:205], v[142:143], 0, s[8:9]
	v_mfma_f32_16x16x32_bf16 v[30:33], v[208:211], v[232:235], v[30:33]
	global_load_lds_dwordx4 v[204:205], off
	v_mfma_f32_16x16x32_bf16 v[26:29], v[178:181], v[236:239], v[26:29]
	s_mov_b32 m0, s44
	v_mfma_f32_16x16x32_bf16 v[22:25], v[182:185], v[236:239], v[22:25]
	global_load_lds_dwordx4 v[144:145], off
	v_mfma_f32_16x16x32_bf16 v[18:21], v[200:203], v[236:239], v[18:21]
	s_mov_b32 m0, s45
	v_lshl_add_u64 v[204:205], v[144:145], 0, s[4:5]
	v_mfma_f32_16x16x32_bf16 v[14:17], v[208:211], v[236:239], v[14:17]
	global_load_lds_dwordx4 v[204:205], off
	v_mfma_f32_16x16x32_bf16 v[10:13], v[178:181], v[240:243], v[10:13]
	s_mov_b32 m0, s46
	v_lshl_add_u64 v[204:205], v[144:145], 0, s[6:7]
	v_mfma_f32_16x16x32_bf16 v[6:9], v[182:185], v[240:243], v[6:9]
	global_load_lds_dwordx4 v[204:205], off
	v_mfma_f32_16x16x32_bf16 v[2:5], v[200:203], v[240:243], v[2:5]
	s_mov_b32 m0, s47
	v_lshl_add_u64 v[204:205], v[144:145], 0, s[8:9]
	v_mfma_f32_16x16x32_bf16 v[38:41], v[208:211], v[240:243], v[38:41]
	global_load_lds_dwordx4 v[204:205], off
	v_lshl_add_u64 v[142:143], v[142:143], 0, s[10:11]
	v_lshl_add_u64 v[144:145], v[144:145], 0, s[10:11]
	s_waitcnt lgkmcnt(6)
	v_mfma_f32_16x16x32_bf16 v[126:129], v[162:165], v[212:215], v[126:129]
	ds_read_b128 v[228:231], v245 offset:8192
	s_waitcnt lgkmcnt(6)
	v_mfma_f32_16x16x32_bf16 v[122:125], v[166:169], v[212:215], v[122:125]
	ds_read_b128 v[232:235], v245 offset:10240
	s_waitcnt lgkmcnt(6)
	v_mfma_f32_16x16x32_bf16 v[118:121], v[170:173], v[212:215], v[118:121]
	s_waitcnt lgkmcnt(5)
	v_mfma_f32_16x16x32_bf16 v[114:117], v[174:177], v[212:215], v[114:117]
	s_waitcnt lgkmcnt(4)
	v_mfma_f32_16x16x32_bf16 v[110:113], v[162:165], v[216:219], v[110:113]
	v_mfma_f32_16x16x32_bf16 v[106:109], v[166:169], v[216:219], v[106:109]
	v_mfma_f32_16x16x32_bf16 v[102:105], v[170:173], v[216:219], v[102:105]
	v_mfma_f32_16x16x32_bf16 v[98:101], v[174:177], v[216:219], v[98:101]
	s_waitcnt lgkmcnt(3)
	v_mfma_f32_16x16x32_bf16 v[94:97], v[162:165], v[220:223], v[94:97]
	ds_read_b128 v[236:239], v245 offset:12288
	v_mfma_f32_16x16x32_bf16 v[90:93], v[166:169], v[220:223], v[90:93]
	ds_read_b128 v[240:243], v245 offset:14336
	v_mfma_f32_16x16x32_bf16 v[86:89], v[170:173], v[220:223], v[86:89]
	v_mfma_f32_16x16x32_bf16 v[82:85], v[174:177], v[220:223], v[82:85]
	s_waitcnt lgkmcnt(4)
	v_mfma_f32_16x16x32_bf16 v[78:81], v[162:165], v[224:227], v[78:81]
	v_mfma_f32_16x16x32_bf16 v[74:77], v[166:169], v[224:227], v[74:77]
	v_mfma_f32_16x16x32_bf16 v[70:73], v[170:173], v[224:227], v[70:73]
	v_mfma_f32_16x16x32_bf16 v[66:69], v[174:177], v[224:227], v[66:69]
	s_waitcnt lgkmcnt(3)
	v_mfma_f32_16x16x32_bf16 v[62:65], v[162:165], v[228:231], v[62:65]
	ds_read_b128 v[178:181], v246 offset:32768
	v_mfma_f32_16x16x32_bf16 v[58:61], v[166:169], v[228:231], v[58:61]
	ds_read_b128 v[182:185], v246 offset:34816
	v_mfma_f32_16x16x32_bf16 v[54:57], v[170:173], v[228:231], v[54:57]
	ds_read_b128 v[200:203], v246 offset:36864
	v_mfma_f32_16x16x32_bf16 v[50:53], v[174:177], v[228:231], v[50:53]
	ds_read_b128 v[208:211], v246 offset:38912
	s_waitcnt lgkmcnt(6)
	v_mfma_f32_16x16x32_bf16 v[46:49], v[162:165], v[232:235], v[46:49]
	ds_read_b128 v[212:215], v247
	v_mfma_f32_16x16x32_bf16 v[42:45], v[166:169], v[232:235], v[42:45]
	ds_read_b128 v[216:219], v247 offset:2048
	v_mfma_f32_16x16x32_bf16 v[34:37], v[170:173], v[232:235], v[34:37]
	v_mfma_f32_16x16x32_bf16 v[30:33], v[174:177], v[232:235], v[30:33]
	s_waitcnt lgkmcnt(7)
	v_mfma_f32_16x16x32_bf16 v[26:29], v[162:165], v[236:239], v[26:29]
	ds_read_b128 v[220:223], v247 offset:4096
	v_mfma_f32_16x16x32_bf16 v[22:25], v[166:169], v[236:239], v[22:25]
	ds_read_b128 v[224:227], v247 offset:6144
	v_mfma_f32_16x16x32_bf16 v[18:21], v[170:173], v[236:239], v[18:21]
	v_mfma_f32_16x16x32_bf16 v[14:17], v[174:177], v[236:239], v[14:17]
	s_waitcnt lgkmcnt(8)
; #define GLDS_STAGE(st, kt_) do { \
;         _Pragma("unroll") for (int i_ = 0; i_ < FI; ++i_) { \
;             glds16(ap + (size_t)(32 * i_) * lda + (kt_) * 64, l3a + (st) + tid * 16 + i_ * 4096); \
;             glds16(bp + (size_t)(32 * i_) * ldb + (kt_) * 64, l3a + (st) + OPB + tid * 16 + i_ * 4096); } } while (0)
; #define GLDS_STAGE(st, kt_) do { \
;         _Pragma("unroll") for (int i_ = 0; i_ < 4; ++i_) { \
;             glds16(ap + (size_t)(64 * i_) * lda + (kt_) * 64, l3a + (st) + tid * 16 + i_ * 8192); \
;             glds16(bp + (size_t)(64 * i_) * ldb + (kt_) * 64, l3a + (st) + 32768 + tid * 16 + i_ * 8192); } } while (0)
; template <class Epi>
; DEV void gemm256_tile(const bf16_t* __restrict__ A, int lda, const bf16_t* __restrict__ Bt, int ldb, int K, unsigned char* lds, const Epi& epi) {
;     ...
;     for (int kt = 0; kt < nk; ++kt) {
;         const int cur = (kt & 1) * 65536;
;         asm volatile("s_waitcnt vmcnt(0)" ::: "memory");
;         __syncthreads();
;         if (kt + 1 < nk) GLDS_STAGE(cur ^ 65536, kt + 1);
; #pragma unroll
;         for (int kh = 0; kh < 2; ++kh) {
;             bf16x8 bfr[4];
;             const int ch = ((kh * 4 + fq) ^ sw) << 4;
; #pragma unroll
;             for (int i = 0; i < 4; ++i) bfr[i] = *(const bf16x8*)(lds + cur + boff + i * 2048 + ch);
; #pragma unroll
;             for (int mh = 0; mh < 2; ++mh) {
;                 bf16x8 af[4];
; #pragma unroll
;                 for (int i = 0; i < 4; ++i) af[i] = *(const bf16x8*)(lds + cur + aoff + (mh * 4 + i) * 2048 + ch);
; #pragma unroll
;                 for (int mi = 0; mi < 4; ++mi)
; #pragma unroll
;                     for (int ni = 0; ni < 4; ++ni) acc[mh * 4 + mi][ni] = __builtin_amdgcn_mfma_f32_16x16x32_bf16(bfr[ni], af[mi], acc[mh * 4 + mi][ni], 0, 0, 0);
;             }
;         }
	v_mfma_f32_16x16x32_bf16 v[10:13], v[162:165], v[240:243], v[10:13]
	v_mfma_f32_16x16x32_bf16 v[6:9], v[166:169], v[240:243], v[6:9]
	v_mfma_f32_16x16x32_bf16 v[2:5], v[170:173], v[240:243], v[2:5]
	v_mfma_f32_16x16x32_bf16 v[38:41], v[174:177], v[240:243], v[38:41]
	s_waitcnt lgkmcnt(3)
	v_mfma_f32_16x16x32_bf16 v[126:129], v[178:181], v[212:215], v[126:129]
	ds_read_b128 v[228:231], v247 offset:8192
	v_mfma_f32_16x16x32_bf16 v[122:125], v[182:185], v[212:215], v[122:125]
	ds_read_b128 v[232:235], v247 offset:10240
	v_mfma_f32_16x16x32_bf16 v[118:121], v[200:203], v[212:215], v[118:121]
	v_mfma_f32_16x16x32_bf16 v[114:117], v[208:211], v[212:215], v[114:117]
	s_waitcnt lgkmcnt(4)
	v_mfma_f32_16x16x32_bf16 v[110:113], v[178:181], v[216:219], v[110:113]
	v_mfma_f32_16x16x32_bf16 v[106:109], v[182:185], v[216:219], v[106:109]
	v_mfma_f32_16x16x32_bf16 v[102:105], v[200:203], v[216:219], v[102:105]
	v_mfma_f32_16x16x32_bf16 v[98:101], v[208:211], v[216:219], v[98:101]
	s_waitcnt lgkmcnt(3)
	v_mfma_f32_16x16x32_bf16 v[94:97], v[178:181], v[220:223], v[94:97]
	ds_read_b128 v[236:239], v247 offset:12288
	v_mfma_f32_16x16x32_bf16 v[90:93], v[182:185], v[220:223], v[90:93]
	ds_read_b128 v[240:243], v247 offset:14336
	v_mfma_f32_16x16x32_bf16 v[86:89], v[200:203], v[220:223], v[86:89]
	v_mfma_f32_16x16x32_bf16 v[82:85], v[208:211], v[220:223], v[82:85]
	s_waitcnt lgkmcnt(4)
	v_mfma_f32_16x16x32_bf16 v[78:81], v[178:181], v[224:227], v[78:81]
	v_mfma_f32_16x16x32_bf16 v[74:77], v[182:185], v[224:227], v[74:77]
	v_mfma_f32_16x16x32_bf16 v[70:73], v[200:203], v[224:227], v[70:73]
	v_mfma_f32_16x16x32_bf16 v[66:69], v[208:211], v[224:227], v[66:69]
	s_add_i32 s21, s21, 0x10000
	s_cmp_eq_u32 s21, 0x1f0000
	s_cbranch_scc0 .Lg256r_d
	s_waitcnt lgkmcnt(0)
	v_mfma_f32_16x16x32_bf16 v[62:65], v[178:181], v[228:231], v[62:65]
	v_mfma_f32_16x16x32_bf16 v[58:61], v[182:185], v[228:231], v[58:61]
	v_mfma_f32_16x16x32_bf16 v[54:57], v[200:203], v[228:231], v[54:57]
	v_mfma_f32_16x16x32_bf16 v[50:53], v[208:211], v[228:231], v[50:53]
	v_mfma_f32_16x16x32_bf16 v[46:49], v[178:181], v[232:235], v[46:49]
	v_mfma_f32_16x16x32_bf16 v[42:45], v[182:185], v[232:235], v[42:45]
	v_mfma_f32_16x16x32_bf16 v[34:37], v[200:203], v[232:235], v[34:37]
	v_mfma_f32_16x16x32_bf16 v[30:33], v[208:211], v[232:235], v[30:33]
	v_mfma_f32_16x16x32_bf16 v[26:29], v[178:181], v[236:239], v[26:29]
	v_mfma_f32_16x16x32_bf16 v[22:25], v[182:185], v[236:239], v[22:25]
	v_mfma_f32_16x16x32_bf16 v[18:21], v[200:203], v[236:239], v[18:21]
	v_mfma_f32_16x16x32_bf16 v[14:17], v[208:211], v[236:239], v[14:17]
	v_mfma_f32_16x16x32_bf16 v[10:13], v[178:181], v[240:243], v[10:13]
	v_mfma_f32_16x16x32_bf16 v[6:9], v[182:185], v[240:243], v[6:9]
	v_mfma_f32_16x16x32_bf16 v[2:5], v[200:203], v[240:243], v[2:5]
	v_mfma_f32_16x16x32_bf16 v[38:41], v[208:211], v[240:243], v[38:41]
	v_or_b32_e32 v184, 0x18000, v155
	v_add_u32_e32 v156, v184, v154
	s_waitcnt vmcnt(0)
	s_barrier
	ds_read_b128 v[142:145], v156
	ds_read_b128 v[162:165], v156 offset:2048
	ds_read_b128 v[166:169], v156 offset:4096
	ds_read_b128 v[170:173], v156 offset:6144
	v_add_u32_e32 v198, 0x10000, v152
	v_add_u32_e32 v178, v198, v154
	ds_read_b128 v[152:155], v178
	s_waitcnt lgkmcnt(0)
	v_mfma_f32_16x16x32_bf16 v[126:129], v[142:145], v[152:155], v[126:129]
	s_sext_i32_i8 s14, s20
	s_lshl_b32 s20, s14, 8
	s_ashr_i32 s21, s20, 31
	v_mfma_f32_16x16x32_bf16 v[122:125], v[162:165], v[152:155], v[122:125]
	v_lshl_add_u64 v[156:157], v[134:135], 0, s[12:13]
	v_lshl_add_u64 v[182:183], v[130:131], 0, s[12:13]
	s_lshl_b64 s[12:13], s[20:21], 1
	v_mfma_f32_16x16x32_bf16 v[118:121], v[166:169], v[152:155], v[118:121]
	v_lshlrev_b32_e32 v148, 3, v148
	v_lshlrev_b32_e32 v150, 9, v150
	v_and_or_b32 v148, v148, 8, v150
	v_mfma_f32_16x16x32_bf16 v[114:117], v[170:173], v[152:155], v[114:117]
	ds_read_b128 v[152:155], v178 offset:2048
	s_waitcnt lgkmcnt(0)
	v_mfma_f32_16x16x32_bf16 v[110:113], v[142:145], v[152:155], v[110:113]
	v_mfma_f32_16x16x32_bf16 v[106:109], v[162:165], v[152:155], v[106:109]
	v_mfma_f32_16x16x32_bf16 v[102:105], v[166:169], v[152:155], v[102:105]
	v_mfma_f32_16x16x32_bf16 v[98:101], v[170:173], v[152:155], v[98:101]
	ds_read_b128 v[152:155], v178 offset:4096
	s_waitcnt lgkmcnt(0)
	v_mfma_f32_16x16x32_bf16 v[94:97], v[142:145], v[152:155], v[94:97]
	v_mfma_f32_16x16x32_bf16 v[90:93], v[162:165], v[152:155], v[90:93]
	v_mfma_f32_16x16x32_bf16 v[86:89], v[166:169], v[152:155], v[86:89]
	v_mfma_f32_16x16x32_bf16 v[82:85], v[170:173], v[152:155], v[82:85]
	ds_read_b128 v[152:155], v178 offset:6144
	s_waitcnt lgkmcnt(0)
	v_mfma_f32_16x16x32_bf16 v[78:81], v[142:145], v[152:155], v[78:81]
	v_mfma_f32_16x16x32_bf16 v[74:77], v[162:165], v[152:155], v[74:77]
	v_mfma_f32_16x16x32_bf16 v[70:73], v[166:169], v[152:155], v[70:73]
	v_mfma_f32_16x16x32_bf16 v[66:69], v[170:173], v[152:155], v[66:69]
	ds_read_b128 v[152:155], v178 offset:8192
	ds_read_b128 v[174:177], v178 offset:10240
	s_waitcnt lgkmcnt(1)
	v_mfma_f32_16x16x32_bf16 v[62:65], v[142:145], v[152:155], v[62:65]
	v_mfma_f32_16x16x32_bf16 v[58:61], v[162:165], v[152:155], v[58:61]
	v_mfma_f32_16x16x32_bf16 v[54:57], v[166:169], v[152:155], v[54:57]
	v_mfma_f32_16x16x32_bf16 v[50:53], v[170:173], v[152:155], v[50:53]
	ds_read_b128 v[152:155], v178 offset:12288
	s_waitcnt lgkmcnt(1)
	v_mfma_f32_16x16x32_bf16 v[46:49], v[142:145], v[174:177], v[46:49]
	v_mfma_f32_16x16x32_bf16 v[42:45], v[162:165], v[174:177], v[42:45]
	v_mfma_f32_16x16x32_bf16 v[34:37], v[166:169], v[174:177], v[34:37]
	v_mfma_f32_16x16x32_bf16 v[30:33], v[170:173], v[174:177], v[30:33]
	ds_read_b128 v[174:177], v178 offset:14336
	s_waitcnt lgkmcnt(1)
	v_mfma_f32_16x16x32_bf16 v[178:181], v[142:145], v[152:155], v[26:29]
	s_nop 2
	v_lshl_add_u64 v[28:29], v[156:157], 0, s[12:13]
	v_add_u32_e32 v157, v184, v151
	v_lshl_add_u64 v[26:27], v[182:183], 0, s[12:13]
	ds_read_b128 v[182:185], v157
	ds_read_b128 v[186:189], v157 offset:2048
	ds_read_b128 v[190:193], v157 offset:4096
	ds_read_b128 v[194:197], v157 offset:6144
	v_add_u32_e32 v151, v198, v151
	v_mfma_f32_16x16x32_bf16 v[22:25], v[162:165], v[152:155], v[22:25]
	v_and_b32_e32 v156, 0xc0, v146
	v_lshl_or_b32 v149, v149, 2, v156
	s_mov_b32 s12, 0
	v_mfma_f32_16x16x32_bf16 v[18:21], v[166:169], v[152:155], v[18:21]
	v_mfma_f32_16x16x32_bf16 v[14:17], v[170:173], v[152:155], v[14:17]
	ds_read_b128 v[152:155], v151
	ds_read_b128 v[198:201], v151 offset:2048
	ds_read_b128 v[202:205], v151 offset:4096
	ds_read_b128 v[206:209], v151 offset:6144
	s_waitcnt lgkmcnt(8)
	v_mfma_f32_16x16x32_bf16 v[10:13], v[142:145], v[174:177], v[10:13]
	ds_read_b128 v[142:145], v151 offset:8192
	ds_read_b128 v[210:213], v151 offset:10240
	ds_read_b128 v[214:217], v151 offset:12288
	ds_read_b128 v[218:221], v151 offset:14336
	s_waitcnt lgkmcnt(0)
	s_barrier
; DEV unsigned cvt_pk_bf16(float lo, float hi) { const f32x2_t v = {lo, hi}; const bf16x2_t b = __builtin_convertvector(v, bf16x2_t); return __builtin_bit_cast(unsigned, b); }
; template <class Epi>
; DEV void gemm256_tile(const bf16_t* __restrict__ A, int lda, const bf16_t* __restrict__ Bt, int ldb, int K, unsigned char* lds, const Epi& epi) {
;     ...
;                 for (int i = 0; i < 4; ++i) af[i] = *(const bf16x8*)(lds + cur + aoff + (mh * 4 + i) * 2048 + ch);
; #pragma unroll
;                 for (int mi = 0; mi < 4; ++mi)
; #pragma unroll
;                     for (int ni = 0; ni < 4; ++ni) acc[mh * 4 + mi][ni] = __builtin_amdgcn_mfma_f32_16x16x32_bf16(bfr[ni], af[mi], acc[mh * 4 + mi][ni], 0, 0, 0);
;             }
;         }
;     }
;     ...
;     __syncthreads();
;     if constexpr (Epi::STAGE) {
; #pragma unroll
;         for (int mi = 0; mi < 8; ++mi)
; #pragma unroll
;             for (int ni = 0; ni < 4; ++ni) {
;                 const int row = wr * 128 + mi * 16 + fr, col = wc * 64 + ni * 16 + fq * 4;
;                 const f32x4 v = epi.xform(row, col, acc[mi][ni]);
;                 uint2 w; w.x = cvt_pk_bf16(v[0], v[1]); w.y = cvt_pk_bf16(v[2], v[3]);
;                 *(uint2*)(lds + row * 512 + ((((col >> 3) ^ (row & 31)) << 4) | (((col >> 2) & 1) << 3))) = w;
	v_mfma_f32_16x16x32_bf16 v[2:5], v[166:169], v[174:177], v[2:5]
	v_mfma_f32_16x16x32_bf16 v[126:129], v[182:185], v[152:155], v[126:129]
	v_mfma_f32_16x16x32_bf16 v[114:117], v[194:197], v[152:155], v[114:117]
	v_mfma_f32_16x16x32_bf16 v[102:105], v[190:193], v[198:201], v[102:105]
	s_nop 5
	v_cvt_pk_bf16_f32 v126, v126, v127
	v_cvt_pk_bf16_f32 v127, v128, v129
	v_lshrrev_b32_e32 v128, 3, v149
	v_mfma_f32_16x16x32_bf16 v[34:37], v[190:193], v[210:213], v[34:37]
	v_cvt_pk_bf16_f32 v114, v114, v115
	v_cvt_pk_bf16_f32 v115, v116, v117
	v_or_b32_e32 v117, 16, v147
	v_mfma_f32_16x16x32_bf16 v[2:5], v[190:193], v[218:221], v[2:5]
	v_cvt_pk_bf16_f32 v102, v102, v103
	v_cvt_pk_bf16_f32 v103, v104, v105
	v_bitop3_b32 v104, v128, v117, 4 bitop3:0x36
	v_mfma_f32_16x16x32_bf16 v[38:41], v[170:173], v[174:177], v[38:41]
	v_lshl_add_u32 v104, v104, 4, v148
	v_cvt_pk_bf16_f32 v34, v34, v35
	v_cvt_pk_bf16_f32 v35, v36, v37
	v_mfma_f32_16x16x32_bf16 v[6:9], v[162:165], v[174:177], v[6:9]
	v_cvt_pk_bf16_f32 v2, v2, v3
	v_cvt_pk_bf16_f32 v3, v4, v5
	ds_write2st64_b64 v104, v[34:35], v[2:3] offset0:80 offset1:112
	v_mfma_f32_16x16x32_bf16 v[30:33], v[194:197], v[210:213], v[30:33]
	v_xor_b32_e32 v129, v128, v147
	v_bitop3_b32 v116, v128, v147, 6 bitop3:0x36
	v_lshl_or_b32 v129, v129, 4, v148
	v_mfma_f32_16x16x32_bf16 v[98:101], v[194:197], v[198:201], v[98:101]
	v_lshl_add_u32 v116, v116, 4, v148
	s_nop 2
	v_cvt_pk_bf16_f32 v36, v30, v31
	v_cvt_pk_bf16_f32 v37, v32, v33
	v_mfma_f32_16x16x32_bf16 v[122:125], v[186:189], v[152:155], v[122:125]
	v_mfma_f32_16x16x32_bf16 v[118:121], v[190:193], v[152:155], v[118:121]
	v_cvt_pk_bf16_f32 v98, v98, v99
	v_cvt_pk_bf16_f32 v99, v100, v101
	v_bitop3_b32 v100, v128, v117, 6 bitop3:0x36
	v_mfma_f32_16x16x32_bf16 v[110:113], v[182:185], v[198:201], v[110:113]
	s_nop 2
	v_cvt_pk_bf16_f32 v122, v122, v123
	v_cvt_pk_bf16_f32 v123, v124, v125
	v_bitop3_b32 v124, v128, v147, 2 bitop3:0x36
	v_mfma_f32_16x16x32_bf16 v[106:109], v[186:189], v[198:201], v[106:109]
	v_cvt_pk_bf16_f32 v118, v118, v119
	v_cvt_pk_bf16_f32 v119, v120, v121
	v_bitop3_b32 v120, v128, v147, 4 bitop3:0x36
	v_mfma_f32_16x16x32_bf16 v[2:5], v[194:197], v[218:221], v[38:41]
	v_cvt_pk_bf16_f32 v110, v110, v111
	v_cvt_pk_bf16_f32 v111, v112, v113
	v_bitop3_b32 v112, v128, v147, 16 bitop3:0x1e
	v_mfma_f32_16x16x32_bf16 v[94:97], v[182:185], v[202:205], v[94:97]
	v_cvt_pk_bf16_f32 v106, v106, v107
	v_cvt_pk_bf16_f32 v107, v108, v109
	v_bitop3_b32 v108, v128, v117, 2 bitop3:0x36
	v_mfma_f32_16x16x32_bf16 v[90:93], v[186:189], v[202:205], v[90:93]
	v_lshl_add_u32 v100, v100, 4, v148
	v_cvt_pk_bf16_f32 v2, v2, v3
	v_cvt_pk_bf16_f32 v3, v4, v5
	v_mfma_f32_16x16x32_bf16 v[86:89], v[190:193], v[202:205], v[86:89]
	v_lshl_add_u32 v124, v124, 4, v148
	v_lshl_add_u32 v120, v120, 4, v148
	v_lshl_or_b32 v112, v112, 4, v148
	v_mfma_f32_16x16x32_bf16 v[82:85], v[194:197], v[202:205], v[82:85]
	v_lshl_add_u32 v108, v108, 4, v148
	v_cvt_pk_bf16_f32 v94, v94, v95
	v_cvt_pk_bf16_f32 v95, v96, v97
	v_mfma_f32_16x16x32_bf16 v[78:81], v[182:185], v[206:209], v[78:81]
	v_cvt_pk_bf16_f32 v90, v90, v91
	v_cvt_pk_bf16_f32 v91, v92, v93
	v_cvt_pk_bf16_f32 v86, v86, v87
	v_mfma_f32_16x16x32_bf16 v[74:77], v[186:189], v[206:209], v[74:77]
	v_cvt_pk_bf16_f32 v87, v88, v89
	v_cvt_pk_bf16_f32 v82, v82, v83
	v_cvt_pk_bf16_f32 v83, v84, v85
	v_mfma_f32_16x16x32_bf16 v[70:73], v[190:193], v[206:209], v[70:73]
	v_cvt_pk_bf16_f32 v78, v78, v79
	v_cvt_pk_bf16_f32 v79, v80, v81
	s_nop 1
	v_cvt_pk_bf16_f32 v74, v74, v75
	v_mfma_f32_16x16x32_bf16 v[66:69], v[194:197], v[206:209], v[66:69]
	v_cvt_pk_bf16_f32 v75, v76, v77
	s_nop 0
	v_cvt_pk_bf16_f32 v70, v70, v71
	v_cvt_pk_bf16_f32 v71, v72, v73
	v_mfma_f32_16x16x32_bf16 v[62:65], v[182:185], v[142:145], v[62:65]
	ds_write2st64_b64 v100, v[36:37], v[2:3] offset0:80 offset1:112
	s_nop 1
	v_cvt_pk_bf16_f32 v66, v66, v67
	v_cvt_pk_bf16_f32 v67, v68, v69
	v_mfma_f32_16x16x32_bf16 v[58:61], v[186:189], v[142:145], v[58:61]
	v_and_b32_e32 v2, 0x1f0, v140
	s_nop 0
	v_cvt_pk_bf16_f32 v62, v62, v63
	v_cvt_pk_bf16_f32 v63, v64, v65
	v_mfma_f32_16x16x32_bf16 v[54:57], v[190:193], v[142:145], v[54:57]
	ds_write2st64_b64 v129, v[126:127], v[94:95] offset1:32
	s_nop 1
	v_cvt_pk_bf16_f32 v58, v58, v59
	v_cvt_pk_bf16_f32 v59, v60, v61
	v_mfma_f32_16x16x32_bf16 v[50:53], v[194:197], v[142:145], v[50:53]
	ds_write2st64_b64 v124, v[122:123], v[90:91] offset1:32
	s_nop 0
	v_cvt_pk_bf16_f32 v54, v54, v55
	v_cvt_pk_bf16_f32 v55, v56, v57
	v_mfma_f32_16x16x32_bf16 v[46:49], v[182:185], v[210:213], v[46:49]
	ds_write2st64_b64 v120, v[118:119], v[86:87] offset1:32
	s_nop 1
	v_cvt_pk_bf16_f32 v50, v50, v51
	v_cvt_pk_bf16_f32 v51, v52, v53
	v_mfma_f32_16x16x32_bf16 v[42:45], v[186:189], v[210:213], v[42:45]
	ds_write2st64_b64 v116, v[114:115], v[82:83] offset1:32
	s_nop 0
	v_cvt_pk_bf16_f32 v46, v46, v47
	v_cvt_pk_bf16_f32 v47, v48, v49
	v_mfma_f32_16x16x32_bf16 v[30:33], v[182:185], v[214:217], v[178:181]
	ds_write2st64_b64 v112, v[110:111], v[78:79] offset0:16 offset1:48
	s_nop 1
	v_cvt_pk_bf16_f32 v42, v42, v43
	v_cvt_pk_bf16_f32 v43, v44, v45
	v_mfma_f32_16x16x32_bf16 v[22:25], v[186:189], v[214:217], v[22:25]
	ds_write2st64_b64 v108, v[106:107], v[74:75] offset0:16 offset1:48
	s_nop 0
	v_cvt_pk_bf16_f32 v30, v30, v31
	v_cvt_pk_bf16_f32 v31, v32, v33
	v_mfma_f32_16x16x32_bf16 v[18:21], v[190:193], v[214:217], v[18:21]
	ds_write2st64_b64 v104, v[102:103], v[70:71] offset0:16 offset1:48
	s_nop 1
	v_cvt_pk_bf16_f32 v22, v22, v23
	v_cvt_pk_bf16_f32 v23, v24, v25
	v_mfma_f32_16x16x32_bf16 v[14:17], v[194:197], v[214:217], v[14:17]
	ds_write2st64_b64 v100, v[98:99], v[66:67] offset0:16 offset1:48
	s_nop 0
	v_cvt_pk_bf16_f32 v18, v18, v19
	v_cvt_pk_bf16_f32 v19, v20, v21
	v_mfma_f32_16x16x32_bf16 v[10:13], v[182:185], v[218:221], v[10:13]
	ds_write2st64_b64 v129, v[62:63], v[30:31] offset0:64 offset1:96
	s_nop 1
	v_cvt_pk_bf16_f32 v14, v14, v15
	v_cvt_pk_bf16_f32 v15, v16, v17
	v_mfma_f32_16x16x32_bf16 v[6:9], v[186:189], v[218:221], v[6:9]
	ds_write2st64_b64 v124, v[58:59], v[22:23] offset0:64 offset1:96
	s_nop 0
	v_cvt_pk_bf16_f32 v10, v10, v11
	v_cvt_pk_bf16_f32 v11, v12, v13
	ds_write2st64_b64 v120, v[54:55], v[18:19] offset0:64 offset1:96
	ds_write2st64_b64 v116, v[50:51], v[14:15] offset0:64 offset1:96
	s_nop 1
	v_cvt_pk_bf16_f32 v6, v6, v7
	v_cvt_pk_bf16_f32 v7, v8, v9
	ds_write2st64_b64 v112, v[46:47], v[10:11] offset0:80 offset1:112
	ds_write2st64_b64 v108, v[42:43], v[6:7] offset0:80 offset1:112
	s_waitcnt lgkmcnt(0)
	s_barrier
